# loop-edge edit: K-loop back-edge scalar updates hoisted into the preceding load segment (8 GEMM loops)
# baseline (speedup 1.0000x reference)
.LBB0_189:
	ds_read_b128 v[156:159], v152
	ds_read_b128 v[160:163], v152 offset:1024
	ds_read_b128 v[164:167], v152 offset:2048
	ds_read_b128 v[168:171], v152 offset:3072
	ds_read_b128 v[172:175], v153
	ds_read_b128 v[176:179], v153 offset:1024
	ds_read_b128 v[180:183], v153 offset:2048
	ds_read_b128 v[184:187], v153 offset:3072
	s_add_u32 s82, s80, 0xfffc0080
	s_addc_u32 s83, s81, -1
	s_cmp_eq_u32 s96, 12
	s_cselect_b32 s85, s10, s83
	s_cselect_b32 s84, s11, s82
	s_cselect_b32 s83, s63, s95
	s_cselect_b32 s82, s65, s94
	v_lshl_add_u64 v[144:145], s[80:81], 0, v[136:137]
	s_add_i32 m0, s45, 0xc000
	ds_read_b128 v[188:191], v154
	ds_read_b128 v[192:195], v154 offset:1024
	ds_read_b128 v[200:203], v154 offset:2048
	ds_read_b128 v[204:207], v154 offset:3072
	ds_read_b128 v[208:211], v154 offset:4096
	ds_read_b128 v[212:215], v154 offset:5120
	ds_read_b128 v[216:219], v154 offset:6144
	ds_read_b128 v[224:227], v154 offset:7168
	global_load_lds_dwordx4 v[144:145], off
	v_lshl_add_u64 v[144:145], s[80:81], 0, v[138:139]
	s_add_i32 m0, s45, 0xe000
	s_nop 0
	global_load_lds_dwordx4 v[144:145], off
	s_waitcnt vmcnt(8)
	s_waitcnt lgkmcnt(0)
	s_barrier
	s_setprio 1
	s_waitcnt lgkmcnt(0)
	v_mfma_f32_16x16x32_bf16 v[124:127], v[156:159], v[188:191], v[124:127]
	v_mfma_f32_16x16x32_bf16 v[120:123], v[164:167], v[188:191], v[120:123]
	v_mfma_f32_16x16x32_bf16 v[108:111], v[156:159], v[200:203], v[108:111]
	v_mfma_f32_16x16x32_bf16 v[104:107], v[164:167], v[200:203], v[104:107]
	v_mfma_f32_16x16x32_bf16 v[92:95], v[156:159], v[208:211], v[92:95]
	v_mfma_f32_16x16x32_bf16 v[88:91], v[164:167], v[208:211], v[88:91]
	v_mfma_f32_16x16x32_bf16 v[76:79], v[156:159], v[216:219], v[76:79]
	v_mfma_f32_16x16x32_bf16 v[72:75], v[164:167], v[216:219], v[72:75]
	v_mfma_f32_16x16x32_bf16 v[124:127], v[160:163], v[192:195], v[124:127]
	v_mfma_f32_16x16x32_bf16 v[120:123], v[168:171], v[192:195], v[120:123]
	v_mfma_f32_16x16x32_bf16 v[108:111], v[160:163], v[204:207], v[108:111]
	v_mfma_f32_16x16x32_bf16 v[104:107], v[168:171], v[204:207], v[104:107]
	v_mfma_f32_16x16x32_bf16 v[92:95], v[160:163], v[212:215], v[92:95]
	v_mfma_f32_16x16x32_bf16 v[88:91], v[168:171], v[212:215], v[88:91]
	v_mfma_f32_16x16x32_bf16 v[76:79], v[160:163], v[224:227], v[76:79]
	v_mfma_f32_16x16x32_bf16 v[72:75], v[168:171], v[224:227], v[72:75]
	s_setprio 0
	s_setprio 1
	v_mfma_f32_16x16x32_bf16 v[116:119], v[172:175], v[188:191], v[116:119]
	v_mfma_f32_16x16x32_bf16 v[112:115], v[180:183], v[188:191], v[112:115]
	v_mfma_f32_16x16x32_bf16 v[100:103], v[172:175], v[200:203], v[100:103]
	v_mfma_f32_16x16x32_bf16 v[96:99], v[180:183], v[200:203], v[96:99]
	v_mfma_f32_16x16x32_bf16 v[84:87], v[172:175], v[208:211], v[84:87]
	v_mfma_f32_16x16x32_bf16 v[80:83], v[180:183], v[208:211], v[80:83]
	v_mfma_f32_16x16x32_bf16 v[68:71], v[172:175], v[216:219], v[68:71]
	v_mfma_f32_16x16x32_bf16 v[64:67], v[180:183], v[216:219], v[64:67]
	v_mfma_f32_16x16x32_bf16 v[116:119], v[176:179], v[192:195], v[116:119]
	v_mfma_f32_16x16x32_bf16 v[112:115], v[184:187], v[192:195], v[112:115]
	v_mfma_f32_16x16x32_bf16 v[100:103], v[176:179], v[204:207], v[100:103]
	v_mfma_f32_16x16x32_bf16 v[96:99], v[184:187], v[204:207], v[96:99]
	v_mfma_f32_16x16x32_bf16 v[84:87], v[176:179], v[212:215], v[84:87]
	v_mfma_f32_16x16x32_bf16 v[80:83], v[184:187], v[212:215], v[80:83]
	v_mfma_f32_16x16x32_bf16 v[68:71], v[176:179], v[224:227], v[68:71]
	v_mfma_f32_16x16x32_bf16 v[64:67], v[184:187], v[224:227], v[64:67]
	s_setprio 0
	s_barrier
	s_add_i32 s97, s90, s2
	v_lshl_add_u64 v[144:145], s[82:83], 0, v[132:133]
	s_mov_b32 m0, s97
	ds_read_b128 v[188:191], v154 offset:16384
	ds_read_b128 v[192:195], v154 offset:17408
	ds_read_b128 v[200:203], v154 offset:18432
	ds_read_b128 v[204:207], v154 offset:19456
	ds_read_b128 v[208:211], v154 offset:20480
	ds_read_b128 v[212:215], v154 offset:21504
	ds_read_b128 v[216:219], v154 offset:22528
	ds_read_b128 v[224:227], v154 offset:23552
	global_load_lds_dwordx4 v[144:145], off
	s_add_i32 m0, s97, 0x2000
	s_add_u32 vcc_lo, s82, 0x40000
	v_lshl_add_u64 v[196:197], s[82:83], 0, v[128:129]
	s_addc_u32 vcc_hi, s83, 0
	s_add_i32 s97, s91, s2
	global_load_lds_dwordx4 v[196:197], off
	v_lshl_add_u64 v[220:221], vcc, 0, v[132:133]
	s_mov_b32 m0, s97
	v_lshl_add_u64 v[228:229], s[84:85], 0, v[130:131]
	global_load_lds_dwordx4 v[220:221], off
	v_lshl_add_u64 v[220:221], vcc, 0, v[128:129]
	s_add_i32 m0, s97, 0x2000
	s_nop 0
	global_load_lds_dwordx4 v[220:221], off
	v_lshl_add_u64 v[220:221], s[84:85], 0, v[134:135]
	s_mov_b32 m0, s45
	s_nop 0
	global_load_lds_dwordx4 v[220:221], off
	s_mov_b32 m0, s70
	s_nop 0
	global_load_lds_dwordx4 v[228:229], off
	s_waitcnt vmcnt(8)
	s_waitcnt lgkmcnt(0)
	s_barrier
	s_setprio 1
	s_waitcnt lgkmcnt(0)
	v_mfma_f32_16x16x32_bf16 v[60:63], v[156:159], v[188:191], v[60:63]
	v_mfma_f32_16x16x32_bf16 v[56:59], v[164:167], v[188:191], v[56:59]
	v_mfma_f32_16x16x32_bf16 v[44:47], v[156:159], v[200:203], v[44:47]
	v_mfma_f32_16x16x32_bf16 v[40:43], v[164:167], v[200:203], v[40:43]
	v_mfma_f32_16x16x32_bf16 v[28:31], v[156:159], v[208:211], v[28:31]
	v_mfma_f32_16x16x32_bf16 v[24:27], v[164:167], v[208:211], v[24:27]
	v_mfma_f32_16x16x32_bf16 v[12:15], v[156:159], v[216:219], v[12:15]
	v_mfma_f32_16x16x32_bf16 v[8:11], v[164:167], v[216:219], v[8:11]
	v_mfma_f32_16x16x32_bf16 v[60:63], v[160:163], v[192:195], v[60:63]
	v_mfma_f32_16x16x32_bf16 v[56:59], v[168:171], v[192:195], v[56:59]
	v_mfma_f32_16x16x32_bf16 v[44:47], v[160:163], v[204:207], v[44:47]
	v_mfma_f32_16x16x32_bf16 v[40:43], v[168:171], v[204:207], v[40:43]
	v_mfma_f32_16x16x32_bf16 v[28:31], v[160:163], v[212:215], v[28:31]
	v_mfma_f32_16x16x32_bf16 v[24:27], v[168:171], v[212:215], v[24:27]
	v_mfma_f32_16x16x32_bf16 v[12:15], v[160:163], v[224:227], v[12:15]
	v_mfma_f32_16x16x32_bf16 v[8:11], v[168:171], v[224:227], v[8:11]
	s_setprio 0
	s_setprio 1
	v_mfma_f32_16x16x32_bf16 v[52:55], v[172:175], v[188:191], v[52:55]
	v_mfma_f32_16x16x32_bf16 v[48:51], v[180:183], v[188:191], v[48:51]
	v_mfma_f32_16x16x32_bf16 v[36:39], v[172:175], v[200:203], v[36:39]
	v_mfma_f32_16x16x32_bf16 v[32:35], v[180:183], v[200:203], v[32:35]
	v_mfma_f32_16x16x32_bf16 v[20:23], v[172:175], v[208:211], v[20:23]
	v_mfma_f32_16x16x32_bf16 v[16:19], v[180:183], v[208:211], v[16:19]
	v_mfma_f32_16x16x32_bf16 v[4:7], v[172:175], v[216:219], v[4:7]
	v_mfma_f32_16x16x32_bf16 v[0:3], v[180:183], v[216:219], v[0:3]
	v_mfma_f32_16x16x32_bf16 v[52:55], v[176:179], v[192:195], v[52:55]
	v_mfma_f32_16x16x32_bf16 v[48:51], v[184:187], v[192:195], v[48:51]
	v_mfma_f32_16x16x32_bf16 v[36:39], v[176:179], v[204:207], v[36:39]
	v_mfma_f32_16x16x32_bf16 v[32:35], v[184:187], v[204:207], v[32:35]
	v_mfma_f32_16x16x32_bf16 v[20:23], v[176:179], v[212:215], v[20:23]
	v_mfma_f32_16x16x32_bf16 v[16:19], v[184:187], v[212:215], v[16:19]
	v_mfma_f32_16x16x32_bf16 v[4:7], v[176:179], v[224:227], v[4:7]
	v_mfma_f32_16x16x32_bf16 v[0:3], v[184:187], v[224:227], v[0:3]
	s_setprio 0
	s_barrier
	s_add_i32 s97, 0, 0x18000
	v_add_u32_e32 v155, s97, v147
	s_add_i32 vcc_lo, 0, 0x1c000
	ds_read_b128 v[156:159], v155
	ds_read_b128 v[160:163], v155 offset:1024
	ds_read_b128 v[164:167], v155 offset:2048
	ds_read_b128 v[168:171], v155 offset:3072
	v_add_u32_e32 v155, vcc_lo, v147
	ds_read_b128 v[172:175], v155
	ds_read_b128 v[176:179], v155 offset:1024
	ds_read_b128 v[180:183], v155 offset:2048
	ds_read_b128 v[184:187], v155 offset:3072
	s_add_u32 s84, s84, 0x40000
	s_addc_u32 s85, s85, 0
	s_mov_b32 m0, s71
	v_lshl_add_u64 v[230:231], s[84:85], 0, v[134:135]
	ds_read_b128 v[188:191], v154 offset:32768
	ds_read_b128 v[192:195], v154 offset:33792
	ds_read_b128 v[200:203], v154 offset:34816
	ds_read_b128 v[204:207], v154 offset:35840
	ds_read_b128 v[208:211], v154 offset:36864
	ds_read_b128 v[212:215], v154 offset:37888
	ds_read_b128 v[216:219], v154 offset:38912
	ds_read_b128 v[224:227], v154 offset:39936
	global_load_lds_dwordx4 v[230:231], off
	v_lshl_add_u64 v[230:231], s[84:85], 0, v[130:131]
	s_mov_b32 m0, s75
	s_nop 0
	global_load_lds_dwordx4 v[230:231], off
	s_waitcnt vmcnt(8)
	s_waitcnt lgkmcnt(0)
	s_barrier
	s_setprio 1
	s_waitcnt lgkmcnt(0)
	v_mfma_f32_16x16x32_bf16 v[124:127], v[156:159], v[188:191], v[124:127]
	v_mfma_f32_16x16x32_bf16 v[120:123], v[164:167], v[188:191], v[120:123]
	v_mfma_f32_16x16x32_bf16 v[108:111], v[156:159], v[200:203], v[108:111]
	v_mfma_f32_16x16x32_bf16 v[104:107], v[164:167], v[200:203], v[104:107]
	v_mfma_f32_16x16x32_bf16 v[92:95], v[156:159], v[208:211], v[92:95]
	v_mfma_f32_16x16x32_bf16 v[88:91], v[164:167], v[208:211], v[88:91]
	v_mfma_f32_16x16x32_bf16 v[76:79], v[156:159], v[216:219], v[76:79]
	v_mfma_f32_16x16x32_bf16 v[72:75], v[164:167], v[216:219], v[72:75]
	v_mfma_f32_16x16x32_bf16 v[124:127], v[160:163], v[192:195], v[124:127]
	v_mfma_f32_16x16x32_bf16 v[120:123], v[168:171], v[192:195], v[120:123]
	v_mfma_f32_16x16x32_bf16 v[108:111], v[160:163], v[204:207], v[108:111]
	v_mfma_f32_16x16x32_bf16 v[104:107], v[168:171], v[204:207], v[104:107]
	v_mfma_f32_16x16x32_bf16 v[92:95], v[160:163], v[212:215], v[92:95]
	v_mfma_f32_16x16x32_bf16 v[88:91], v[168:171], v[212:215], v[88:91]
	v_mfma_f32_16x16x32_bf16 v[76:79], v[160:163], v[224:227], v[76:79]
	v_mfma_f32_16x16x32_bf16 v[72:75], v[168:171], v[224:227], v[72:75]
	s_setprio 0
	s_setprio 1
	v_mfma_f32_16x16x32_bf16 v[116:119], v[172:175], v[188:191], v[116:119]
	v_mfma_f32_16x16x32_bf16 v[112:115], v[180:183], v[188:191], v[112:115]
	v_mfma_f32_16x16x32_bf16 v[100:103], v[172:175], v[200:203], v[100:103]
	v_mfma_f32_16x16x32_bf16 v[96:99], v[180:183], v[200:203], v[96:99]
	v_mfma_f32_16x16x32_bf16 v[84:87], v[172:175], v[208:211], v[84:87]
	v_mfma_f32_16x16x32_bf16 v[80:83], v[180:183], v[208:211], v[80:83]
	v_mfma_f32_16x16x32_bf16 v[68:71], v[172:175], v[216:219], v[68:71]
	v_mfma_f32_16x16x32_bf16 v[64:67], v[180:183], v[216:219], v[64:67]
	v_mfma_f32_16x16x32_bf16 v[116:119], v[176:179], v[192:195], v[116:119]
	v_mfma_f32_16x16x32_bf16 v[112:115], v[184:187], v[192:195], v[112:115]
	v_mfma_f32_16x16x32_bf16 v[100:103], v[176:179], v[204:207], v[100:103]
	v_mfma_f32_16x16x32_bf16 v[96:99], v[184:187], v[204:207], v[96:99]
	v_mfma_f32_16x16x32_bf16 v[84:87], v[176:179], v[212:215], v[84:87]
	v_mfma_f32_16x16x32_bf16 v[80:83], v[184:187], v[212:215], v[80:83]
	v_mfma_f32_16x16x32_bf16 v[68:71], v[176:179], v[224:227], v[68:71]
	v_mfma_f32_16x16x32_bf16 v[64:67], v[184:187], v[224:227], v[64:67]
	s_setprio 0
	s_barrier
	s_add_i32 s84, s97, s2
	v_lshl_add_u64 v[144:145], v[144:145], 0, s[8:9]
	s_mov_b32 m0, s84
	ds_read_b128 v[188:191], v154 offset:49152
	ds_read_b128 v[192:195], v154 offset:50176
	ds_read_b128 v[200:203], v154 offset:51200
	ds_read_b128 v[204:207], v154 offset:52224
	ds_read_b128 v[208:211], v154 offset:53248
	ds_read_b128 v[212:215], v154 offset:54272
	ds_read_b128 v[216:219], v154 offset:55296
	ds_read_b128 v[224:227], v154 offset:56320
	global_load_lds_dwordx4 v[144:145], off
	s_add_i32 m0, s84, 0x2000
	s_add_u32 s82, s82, 0x40080
	v_lshl_add_u64 v[144:145], v[196:197], 0, s[8:9]
	s_addc_u32 s83, s83, 0
	s_add_i32 s84, vcc_lo, s2
	global_load_lds_dwordx4 v[144:145], off
	v_lshl_add_u64 v[144:145], s[82:83], 0, v[132:133]
	s_mov_b32 m0, s84
	s_nop 0
	global_load_lds_dwordx4 v[144:145], off
	v_lshl_add_u64 v[144:145], s[82:83], 0, v[128:129]
	s_add_i32 m0, s84, 0x2000
	s_nop 0
	global_load_lds_dwordx4 v[144:145], off
	v_lshl_add_u64 v[144:145], v[220:221], 0, s[8:9]
	s_mov_b32 m0, s86
	s_nop 0
	global_load_lds_dwordx4 v[144:145], off
	v_lshl_add_u64 v[144:145], v[228:229], 0, s[8:9]
	s_mov_b32 m0, s87
	s_nop 0
	global_load_lds_dwordx4 v[144:145], off
	s_add_i32 s96, s96, 2
	s_add_u32 s80, s80, 0x100
	s_addc_u32 s81, s81, 0
	s_add_u32 s94, s94, 0x100
	s_addc_u32 s95, s95, 0
	s_waitcnt vmcnt(8)
	s_waitcnt lgkmcnt(0)
	s_barrier
	s_setprio 1
	s_waitcnt lgkmcnt(0)
	v_mfma_f32_16x16x32_bf16 v[60:63], v[156:159], v[188:191], v[60:63]
	v_mfma_f32_16x16x32_bf16 v[56:59], v[164:167], v[188:191], v[56:59]
	v_mfma_f32_16x16x32_bf16 v[44:47], v[156:159], v[200:203], v[44:47]
	v_mfma_f32_16x16x32_bf16 v[40:43], v[164:167], v[200:203], v[40:43]
	v_mfma_f32_16x16x32_bf16 v[28:31], v[156:159], v[208:211], v[28:31]
	v_mfma_f32_16x16x32_bf16 v[24:27], v[164:167], v[208:211], v[24:27]
	v_mfma_f32_16x16x32_bf16 v[12:15], v[156:159], v[216:219], v[12:15]
	v_mfma_f32_16x16x32_bf16 v[8:11], v[164:167], v[216:219], v[8:11]
	v_mfma_f32_16x16x32_bf16 v[60:63], v[160:163], v[192:195], v[60:63]
	v_mfma_f32_16x16x32_bf16 v[56:59], v[168:171], v[192:195], v[56:59]
	v_mfma_f32_16x16x32_bf16 v[44:47], v[160:163], v[204:207], v[44:47]
	v_mfma_f32_16x16x32_bf16 v[40:43], v[168:171], v[204:207], v[40:43]
	v_mfma_f32_16x16x32_bf16 v[28:31], v[160:163], v[212:215], v[28:31]
	v_mfma_f32_16x16x32_bf16 v[24:27], v[168:171], v[212:215], v[24:27]
	v_mfma_f32_16x16x32_bf16 v[12:15], v[160:163], v[224:227], v[12:15]
	v_mfma_f32_16x16x32_bf16 v[8:11], v[168:171], v[224:227], v[8:11]
	s_setprio 0
	s_setprio 1
	v_mfma_f32_16x16x32_bf16 v[52:55], v[172:175], v[188:191], v[52:55]
	v_mfma_f32_16x16x32_bf16 v[48:51], v[180:183], v[188:191], v[48:51]
	v_mfma_f32_16x16x32_bf16 v[36:39], v[172:175], v[200:203], v[36:39]
	v_mfma_f32_16x16x32_bf16 v[32:35], v[180:183], v[200:203], v[32:35]
	v_mfma_f32_16x16x32_bf16 v[20:23], v[172:175], v[208:211], v[20:23]
	v_mfma_f32_16x16x32_bf16 v[16:19], v[180:183], v[208:211], v[16:19]
	v_mfma_f32_16x16x32_bf16 v[4:7], v[172:175], v[216:219], v[4:7]
	v_mfma_f32_16x16x32_bf16 v[0:3], v[180:183], v[216:219], v[0:3]
	v_mfma_f32_16x16x32_bf16 v[52:55], v[176:179], v[192:195], v[52:55]
	v_mfma_f32_16x16x32_bf16 v[48:51], v[184:187], v[192:195], v[48:51]
	v_mfma_f32_16x16x32_bf16 v[36:39], v[176:179], v[204:207], v[36:39]
	v_mfma_f32_16x16x32_bf16 v[32:35], v[184:187], v[204:207], v[32:35]
	v_mfma_f32_16x16x32_bf16 v[20:23], v[176:179], v[212:215], v[20:23]
	v_mfma_f32_16x16x32_bf16 v[16:19], v[184:187], v[212:215], v[16:19]
	v_mfma_f32_16x16x32_bf16 v[4:7], v[176:179], v[224:227], v[4:7]
	v_mfma_f32_16x16x32_bf16 v[0:3], v[184:187], v[224:227], v[0:3]
	s_setprio 0
	s_barrier
	s_cmp_gt_u32 s96, 13
	s_cbranch_scc0 .LBB0_189
	s_and_b64 vcc, exec, s[60:61]
	s_cbranch_vccz .LBB0_192
	s_barrier

.LBB0_340:
	ds_read_b128 v[144:147], v171
	ds_read_b128 v[148:151], v171 offset:1024
	ds_read_b128 v[152:155], v171 offset:2048
	ds_read_b128 v[156:159], v171 offset:3072
	ds_read_b128 v[160:163], v172
	ds_read_b128 v[164:167], v172 offset:1024
	ds_read_b128 v[176:179], v172 offset:2048
	ds_read_b128 v[180:183], v172 offset:3072
	s_add_u32 s56, s54, 0xfff50080
	s_addc_u32 s57, s55, -1
	s_cmp_eq_u32 s84, 40
	s_cselect_b32 s59, s7, s57
	s_cselect_b32 s58, s6, s56
	s_cselect_b32 s57, s51, s83
	s_cselect_b32 s56, s50, s82
	v_lshl_add_u64 v[196:197], s[54:55], 0, v[136:137]
	s_add_i32 m0, s17, 0xc000
	ds_read_b128 v[184:187], v173
	ds_read_b128 v[188:191], v173 offset:1024
	ds_read_b128 v[192:195], v173 offset:2048
	ds_read_b128 v[200:203], v173 offset:3072
	ds_read_b128 v[204:207], v173 offset:4096
	ds_read_b128 v[208:211], v173 offset:5120
	ds_read_b128 v[212:215], v173 offset:6144
	ds_read_b128 v[216:219], v173 offset:7168
	global_load_lds_dwordx4 v[196:197], off
	v_lshl_add_u64 v[196:197], s[54:55], 0, v[138:139]
	s_add_i32 m0, s17, 0xe000
	s_nop 0
	global_load_lds_dwordx4 v[196:197], off
	s_waitcnt vmcnt(8)
	s_waitcnt lgkmcnt(0)
	s_barrier
	s_setprio 1
	s_waitcnt lgkmcnt(0)
	v_mfma_f32_16x16x32_bf16 v[124:127], v[144:147], v[184:187], v[124:127]
	v_mfma_f32_16x16x32_bf16 v[120:123], v[152:155], v[184:187], v[120:123]
	v_mfma_f32_16x16x32_bf16 v[108:111], v[144:147], v[192:195], v[108:111]
	v_mfma_f32_16x16x32_bf16 v[104:107], v[152:155], v[192:195], v[104:107]
	v_mfma_f32_16x16x32_bf16 v[92:95], v[144:147], v[204:207], v[92:95]
	v_mfma_f32_16x16x32_bf16 v[88:91], v[152:155], v[204:207], v[88:91]
	v_mfma_f32_16x16x32_bf16 v[76:79], v[144:147], v[212:215], v[76:79]
	v_mfma_f32_16x16x32_bf16 v[72:75], v[152:155], v[212:215], v[72:75]
	v_mfma_f32_16x16x32_bf16 v[124:127], v[148:151], v[188:191], v[124:127]
	v_mfma_f32_16x16x32_bf16 v[120:123], v[156:159], v[188:191], v[120:123]
	v_mfma_f32_16x16x32_bf16 v[108:111], v[148:151], v[200:203], v[108:111]
	v_mfma_f32_16x16x32_bf16 v[104:107], v[156:159], v[200:203], v[104:107]
	v_mfma_f32_16x16x32_bf16 v[92:95], v[148:151], v[208:211], v[92:95]
	v_mfma_f32_16x16x32_bf16 v[88:91], v[156:159], v[208:211], v[88:91]
	v_mfma_f32_16x16x32_bf16 v[76:79], v[148:151], v[216:219], v[76:79]
	v_mfma_f32_16x16x32_bf16 v[72:75], v[156:159], v[216:219], v[72:75]
	s_setprio 0
	s_setprio 1
	v_mfma_f32_16x16x32_bf16 v[116:119], v[160:163], v[184:187], v[116:119]
	v_mfma_f32_16x16x32_bf16 v[112:115], v[176:179], v[184:187], v[112:115]
	v_mfma_f32_16x16x32_bf16 v[100:103], v[160:163], v[192:195], v[100:103]
	v_mfma_f32_16x16x32_bf16 v[96:99], v[176:179], v[192:195], v[96:99]
	v_mfma_f32_16x16x32_bf16 v[84:87], v[160:163], v[204:207], v[84:87]
	v_mfma_f32_16x16x32_bf16 v[80:83], v[176:179], v[204:207], v[80:83]
	v_mfma_f32_16x16x32_bf16 v[68:71], v[160:163], v[212:215], v[68:71]
	v_mfma_f32_16x16x32_bf16 v[64:67], v[176:179], v[212:215], v[64:67]
	v_mfma_f32_16x16x32_bf16 v[116:119], v[164:167], v[188:191], v[116:119]
	v_mfma_f32_16x16x32_bf16 v[112:115], v[180:183], v[188:191], v[112:115]
	v_mfma_f32_16x16x32_bf16 v[100:103], v[164:167], v[200:203], v[100:103]
	v_mfma_f32_16x16x32_bf16 v[96:99], v[180:183], v[200:203], v[96:99]
	v_mfma_f32_16x16x32_bf16 v[84:87], v[164:167], v[208:211], v[84:87]
	v_mfma_f32_16x16x32_bf16 v[80:83], v[180:183], v[208:211], v[80:83]
	v_mfma_f32_16x16x32_bf16 v[68:71], v[164:167], v[216:219], v[68:71]
	v_mfma_f32_16x16x32_bf16 v[64:67], v[180:183], v[216:219], v[64:67]
	s_setprio 0
	s_barrier
	s_add_i32 s85, s78, s16
	v_lshl_add_u64 v[196:197], s[56:57], 0, v[130:131]
	s_mov_b32 m0, s85
	ds_read_b128 v[184:187], v173 offset:16384
	ds_read_b128 v[188:191], v173 offset:17408
	ds_read_b128 v[192:195], v173 offset:18432
	ds_read_b128 v[200:203], v173 offset:19456
	ds_read_b128 v[204:207], v173 offset:20480
	ds_read_b128 v[208:211], v173 offset:21504
	ds_read_b128 v[212:215], v173 offset:22528
	ds_read_b128 v[216:219], v173 offset:23552
	global_load_lds_dwordx4 v[196:197], off
	s_add_i32 m0, s85, 0x2000
	s_add_u32 s86, s56, 0xb0000
	v_lshl_add_u64 v[220:221], s[56:57], 0, v[134:135]
	s_addc_u32 s87, s57, 0
	s_add_i32 s85, s79, s16
	global_load_lds_dwordx4 v[220:221], off
	v_lshl_add_u64 v[224:225], s[86:87], 0, v[130:131]
	s_mov_b32 m0, s85
	v_lshl_add_u64 v[226:227], s[58:59], 0, v[132:133]
	global_load_lds_dwordx4 v[224:225], off
	v_lshl_add_u64 v[224:225], s[86:87], 0, v[134:135]
	s_add_i32 m0, s85, 0x2000
	s_nop 0
	global_load_lds_dwordx4 v[224:225], off
	v_lshl_add_u64 v[224:225], s[58:59], 0, v[128:129]
	s_mov_b32 m0, s17
	s_nop 0
	global_load_lds_dwordx4 v[224:225], off
	s_mov_b32 m0, s39
	s_nop 0
	global_load_lds_dwordx4 v[226:227], off
	s_waitcnt vmcnt(8)
	s_waitcnt lgkmcnt(0)
	s_barrier
	s_setprio 1
	s_waitcnt lgkmcnt(0)
	v_mfma_f32_16x16x32_bf16 v[60:63], v[144:147], v[184:187], v[60:63]
	v_mfma_f32_16x16x32_bf16 v[56:59], v[152:155], v[184:187], v[56:59]
	v_mfma_f32_16x16x32_bf16 v[44:47], v[144:147], v[192:195], v[44:47]
	v_mfma_f32_16x16x32_bf16 v[40:43], v[152:155], v[192:195], v[40:43]
	v_mfma_f32_16x16x32_bf16 v[28:31], v[144:147], v[204:207], v[28:31]
	v_mfma_f32_16x16x32_bf16 v[24:27], v[152:155], v[204:207], v[24:27]
	v_mfma_f32_16x16x32_bf16 v[12:15], v[144:147], v[212:215], v[12:15]
	v_mfma_f32_16x16x32_bf16 v[8:11], v[152:155], v[212:215], v[8:11]
	v_mfma_f32_16x16x32_bf16 v[60:63], v[148:151], v[188:191], v[60:63]
	v_mfma_f32_16x16x32_bf16 v[56:59], v[156:159], v[188:191], v[56:59]
	v_mfma_f32_16x16x32_bf16 v[44:47], v[148:151], v[200:203], v[44:47]
	v_mfma_f32_16x16x32_bf16 v[40:43], v[156:159], v[200:203], v[40:43]
	v_mfma_f32_16x16x32_bf16 v[28:31], v[148:151], v[208:211], v[28:31]
	v_mfma_f32_16x16x32_bf16 v[24:27], v[156:159], v[208:211], v[24:27]
	v_mfma_f32_16x16x32_bf16 v[12:15], v[148:151], v[216:219], v[12:15]
	v_mfma_f32_16x16x32_bf16 v[8:11], v[156:159], v[216:219], v[8:11]
	s_setprio 0
	s_setprio 1
	v_mfma_f32_16x16x32_bf16 v[52:55], v[160:163], v[184:187], v[52:55]
	v_mfma_f32_16x16x32_bf16 v[48:51], v[176:179], v[184:187], v[48:51]
	v_mfma_f32_16x16x32_bf16 v[36:39], v[160:163], v[192:195], v[36:39]
	v_mfma_f32_16x16x32_bf16 v[32:35], v[176:179], v[192:195], v[32:35]
	v_mfma_f32_16x16x32_bf16 v[20:23], v[160:163], v[204:207], v[20:23]
	v_mfma_f32_16x16x32_bf16 v[16:19], v[176:179], v[204:207], v[16:19]
	v_mfma_f32_16x16x32_bf16 v[4:7], v[160:163], v[212:215], v[4:7]
	v_mfma_f32_16x16x32_bf16 v[0:3], v[176:179], v[212:215], v[0:3]
	v_mfma_f32_16x16x32_bf16 v[52:55], v[164:167], v[188:191], v[52:55]
	v_mfma_f32_16x16x32_bf16 v[48:51], v[180:183], v[188:191], v[48:51]
	v_mfma_f32_16x16x32_bf16 v[36:39], v[164:167], v[200:203], v[36:39]
	v_mfma_f32_16x16x32_bf16 v[32:35], v[180:183], v[200:203], v[32:35]
	v_mfma_f32_16x16x32_bf16 v[20:23], v[164:167], v[208:211], v[20:23]
	v_mfma_f32_16x16x32_bf16 v[16:19], v[180:183], v[208:211], v[16:19]
	v_mfma_f32_16x16x32_bf16 v[4:7], v[164:167], v[216:219], v[4:7]
	v_mfma_f32_16x16x32_bf16 v[0:3], v[180:183], v[216:219], v[0:3]
	s_setprio 0
	s_barrier
	s_add_i32 s85, 0, 0x18000
	s_add_i32 s86, 0, 0x1c000
	v_add_u32_e32 v156, s85, v169
	v_add_u32_e32 v175, s86, v169
	ds_read_b128 v[144:147], v156
	ds_read_b128 v[148:151], v156 offset:1024
	ds_read_b128 v[152:155], v156 offset:2048
	ds_read_b128 v[156:159], v156 offset:3072
	ds_read_b128 v[160:163], v175
	ds_read_b128 v[164:167], v175 offset:1024
	ds_read_b128 v[176:179], v175 offset:2048
	ds_read_b128 v[180:183], v175 offset:3072
	s_add_u32 s58, s58, 0xb0000
	s_addc_u32 s59, s59, 0
	s_mov_b32 m0, s45
	v_lshl_add_u64 v[228:229], s[58:59], 0, v[128:129]
	ds_read_b128 v[184:187], v173 offset:32768
	ds_read_b128 v[188:191], v173 offset:33792
	ds_read_b128 v[192:195], v173 offset:34816
	ds_read_b128 v[200:203], v173 offset:35840
	ds_read_b128 v[204:207], v173 offset:36864
	ds_read_b128 v[208:211], v173 offset:37888
	ds_read_b128 v[212:215], v173 offset:38912
	ds_read_b128 v[216:219], v173 offset:39936
	global_load_lds_dwordx4 v[228:229], off
	v_lshl_add_u64 v[228:229], s[58:59], 0, v[132:133]
	s_mov_b32 m0, s60
	s_nop 0
	global_load_lds_dwordx4 v[228:229], off
	s_waitcnt vmcnt(8)
	s_waitcnt lgkmcnt(0)
	s_barrier
	s_setprio 1
	s_waitcnt lgkmcnt(0)
	v_mfma_f32_16x16x32_bf16 v[124:127], v[144:147], v[184:187], v[124:127]
	v_mfma_f32_16x16x32_bf16 v[120:123], v[152:155], v[184:187], v[120:123]
	v_mfma_f32_16x16x32_bf16 v[108:111], v[144:147], v[192:195], v[108:111]
	v_mfma_f32_16x16x32_bf16 v[104:107], v[152:155], v[192:195], v[104:107]
	v_mfma_f32_16x16x32_bf16 v[92:95], v[144:147], v[204:207], v[92:95]
	v_mfma_f32_16x16x32_bf16 v[88:91], v[152:155], v[204:207], v[88:91]
	v_mfma_f32_16x16x32_bf16 v[76:79], v[144:147], v[212:215], v[76:79]
	v_mfma_f32_16x16x32_bf16 v[72:75], v[152:155], v[212:215], v[72:75]
	v_mfma_f32_16x16x32_bf16 v[124:127], v[148:151], v[188:191], v[124:127]
	v_mfma_f32_16x16x32_bf16 v[120:123], v[156:159], v[188:191], v[120:123]
	v_mfma_f32_16x16x32_bf16 v[108:111], v[148:151], v[200:203], v[108:111]
	v_mfma_f32_16x16x32_bf16 v[104:107], v[156:159], v[200:203], v[104:107]
	v_mfma_f32_16x16x32_bf16 v[92:95], v[148:151], v[208:211], v[92:95]
	v_mfma_f32_16x16x32_bf16 v[88:91], v[156:159], v[208:211], v[88:91]
	v_mfma_f32_16x16x32_bf16 v[76:79], v[148:151], v[216:219], v[76:79]
	v_mfma_f32_16x16x32_bf16 v[72:75], v[156:159], v[216:219], v[72:75]
	s_setprio 0
	s_setprio 1
	v_mfma_f32_16x16x32_bf16 v[116:119], v[160:163], v[184:187], v[116:119]
	v_mfma_f32_16x16x32_bf16 v[112:115], v[176:179], v[184:187], v[112:115]
	v_mfma_f32_16x16x32_bf16 v[100:103], v[160:163], v[192:195], v[100:103]
	v_mfma_f32_16x16x32_bf16 v[96:99], v[176:179], v[192:195], v[96:99]
	v_mfma_f32_16x16x32_bf16 v[84:87], v[160:163], v[204:207], v[84:87]
	v_mfma_f32_16x16x32_bf16 v[80:83], v[176:179], v[204:207], v[80:83]
	v_mfma_f32_16x16x32_bf16 v[68:71], v[160:163], v[212:215], v[68:71]
	v_mfma_f32_16x16x32_bf16 v[64:67], v[176:179], v[212:215], v[64:67]
	v_mfma_f32_16x16x32_bf16 v[116:119], v[164:167], v[188:191], v[116:119]
	v_mfma_f32_16x16x32_bf16 v[112:115], v[180:183], v[188:191], v[112:115]
	v_mfma_f32_16x16x32_bf16 v[100:103], v[164:167], v[200:203], v[100:103]
	v_mfma_f32_16x16x32_bf16 v[96:99], v[180:183], v[200:203], v[96:99]
	v_mfma_f32_16x16x32_bf16 v[84:87], v[164:167], v[208:211], v[84:87]
	v_mfma_f32_16x16x32_bf16 v[80:83], v[180:183], v[208:211], v[80:83]
	v_mfma_f32_16x16x32_bf16 v[68:71], v[164:167], v[216:219], v[68:71]
	v_mfma_f32_16x16x32_bf16 v[64:67], v[180:183], v[216:219], v[64:67]
	s_setprio 0
	s_barrier
	s_add_i32 s58, s85, s16
	v_lshl_add_u64 v[196:197], v[196:197], 0, s[18:19]
	s_mov_b32 m0, s58
	ds_read_b128 v[184:187], v173 offset:49152
	ds_read_b128 v[188:191], v173 offset:50176
	ds_read_b128 v[192:195], v173 offset:51200
	ds_read_b128 v[200:203], v173 offset:52224
	ds_read_b128 v[204:207], v173 offset:53248
	ds_read_b128 v[208:211], v173 offset:54272
	ds_read_b128 v[212:215], v173 offset:55296
	ds_read_b128 v[216:219], v173 offset:56320
	global_load_lds_dwordx4 v[196:197], off
	s_add_i32 m0, s58, 0x2000
	s_add_u32 s56, s56, 0xb0080
	v_lshl_add_u64 v[196:197], v[220:221], 0, s[18:19]
	s_addc_u32 s57, s57, 0
	s_add_i32 s58, s86, s16
	global_load_lds_dwordx4 v[196:197], off
	v_lshl_add_u64 v[196:197], s[56:57], 0, v[130:131]
	s_mov_b32 m0, s58
	s_nop 0
	global_load_lds_dwordx4 v[196:197], off
	v_lshl_add_u64 v[196:197], s[56:57], 0, v[134:135]
	s_add_i32 m0, s58, 0x2000
	s_nop 0
	global_load_lds_dwordx4 v[196:197], off
	v_lshl_add_u64 v[196:197], v[224:225], 0, s[18:19]
	s_mov_b32 m0, s67
	s_nop 0
	global_load_lds_dwordx4 v[196:197], off
	v_lshl_add_u64 v[196:197], v[226:227], 0, s[18:19]
	s_mov_b32 m0, s70
	s_nop 0
	global_load_lds_dwordx4 v[196:197], off
	s_add_i32 s84, s84, 2
	s_add_u32 s54, s54, 0x100
	s_addc_u32 s55, s55, 0
	s_add_u32 s82, s82, 0x100
	s_addc_u32 s83, s83, 0
	s_waitcnt vmcnt(8)
	s_waitcnt lgkmcnt(0)
	s_barrier
	s_setprio 1
	s_waitcnt lgkmcnt(0)
	v_mfma_f32_16x16x32_bf16 v[60:63], v[144:147], v[184:187], v[60:63]
	v_mfma_f32_16x16x32_bf16 v[56:59], v[152:155], v[184:187], v[56:59]
	v_mfma_f32_16x16x32_bf16 v[44:47], v[144:147], v[192:195], v[44:47]
	v_mfma_f32_16x16x32_bf16 v[40:43], v[152:155], v[192:195], v[40:43]
	v_mfma_f32_16x16x32_bf16 v[28:31], v[144:147], v[204:207], v[28:31]
	v_mfma_f32_16x16x32_bf16 v[24:27], v[152:155], v[204:207], v[24:27]
	v_mfma_f32_16x16x32_bf16 v[12:15], v[144:147], v[212:215], v[12:15]
	v_mfma_f32_16x16x32_bf16 v[8:11], v[152:155], v[212:215], v[8:11]
	v_mfma_f32_16x16x32_bf16 v[60:63], v[148:151], v[188:191], v[60:63]
	v_mfma_f32_16x16x32_bf16 v[56:59], v[156:159], v[188:191], v[56:59]
	v_mfma_f32_16x16x32_bf16 v[44:47], v[148:151], v[200:203], v[44:47]
	v_mfma_f32_16x16x32_bf16 v[40:43], v[156:159], v[200:203], v[40:43]
	v_mfma_f32_16x16x32_bf16 v[28:31], v[148:151], v[208:211], v[28:31]
	v_mfma_f32_16x16x32_bf16 v[24:27], v[156:159], v[208:211], v[24:27]
	v_mfma_f32_16x16x32_bf16 v[12:15], v[148:151], v[216:219], v[12:15]
	v_mfma_f32_16x16x32_bf16 v[8:11], v[156:159], v[216:219], v[8:11]
	s_setprio 0
	s_setprio 1
	v_mfma_f32_16x16x32_bf16 v[52:55], v[160:163], v[184:187], v[52:55]
	v_mfma_f32_16x16x32_bf16 v[48:51], v[176:179], v[184:187], v[48:51]
	v_mfma_f32_16x16x32_bf16 v[36:39], v[160:163], v[192:195], v[36:39]
	v_mfma_f32_16x16x32_bf16 v[32:35], v[176:179], v[192:195], v[32:35]
	v_mfma_f32_16x16x32_bf16 v[20:23], v[160:163], v[204:207], v[20:23]
	v_mfma_f32_16x16x32_bf16 v[16:19], v[176:179], v[204:207], v[16:19]
	v_mfma_f32_16x16x32_bf16 v[4:7], v[160:163], v[212:215], v[4:7]
	v_mfma_f32_16x16x32_bf16 v[0:3], v[176:179], v[212:215], v[0:3]
	v_mfma_f32_16x16x32_bf16 v[52:55], v[164:167], v[188:191], v[52:55]
	v_mfma_f32_16x16x32_bf16 v[48:51], v[180:183], v[188:191], v[48:51]
	v_mfma_f32_16x16x32_bf16 v[36:39], v[164:167], v[200:203], v[36:39]
	v_mfma_f32_16x16x32_bf16 v[32:35], v[180:183], v[200:203], v[32:35]
	v_mfma_f32_16x16x32_bf16 v[20:23], v[164:167], v[208:211], v[20:23]
	v_mfma_f32_16x16x32_bf16 v[16:19], v[180:183], v[208:211], v[16:19]
	v_mfma_f32_16x16x32_bf16 v[4:7], v[164:167], v[216:219], v[4:7]
	v_mfma_f32_16x16x32_bf16 v[0:3], v[180:183], v[216:219], v[0:3]
	s_setprio 0
	s_barrier
	s_cmp_gt_u32 s84, 41
	s_cbranch_scc0 .LBB0_340
	s_and_b64 vcc, exec, s[20:21]
	s_cbranch_vccz .LBB0_343
	s_barrier

.LBB0_476:
	v_add_u32_e32 v164, s71, v188
	ds_read_b128 v[128:131], v210
	ds_read_b128 v[132:135], v210 offset:1024
	ds_read_b128 v[136:139], v210 offset:2048
	ds_read_b128 v[140:143], v210 offset:3072
	ds_read_b128 v[144:147], v164
	ds_read_b128 v[148:151], v164 offset:1024
	ds_read_b128 v[152:155], v164 offset:2048
	ds_read_b128 v[178:181], v164 offset:3072
	s_add_u32 s6, s4, 0xfffc0080
	s_addc_u32 s7, s5, -1
	s_cmp_eq_u32 s91, 12
	s_cselect_b32 s13, s10, s7
	s_cselect_b32 s12, s11, s6
	s_cselect_b32 s7, s20, s90
	s_cselect_b32 s6, s83, s85
	v_lshl_add_u64 v[186:187], s[4:5], 0, v[174:175]
	s_add_i32 m0, s25, 0xc000
	ds_read_b128 v[182:185], v206
	ds_read_b128 v[218:221], v206 offset:1024
	ds_read_b128 v[224:227], v206 offset:2048
	ds_read_b128 v[228:231], v206 offset:3072
	ds_read_b128 v[232:235], v206 offset:4096
	ds_read_b128 v[236:239], v206 offset:5120
	ds_read_b128 v[240:243], v206 offset:6144
	ds_read_b128 v[244:247], v206 offset:7168
	global_load_lds_dwordx4 v[186:187], off
	v_lshl_add_u64 v[186:187], s[4:5], 0, v[176:177]
	s_add_i32 m0, s25, 0xe000
	s_nop 0
	global_load_lds_dwordx4 v[186:187], off
	s_waitcnt vmcnt(8)
	s_waitcnt lgkmcnt(0)
	s_barrier
	s_setprio 1
	s_waitcnt lgkmcnt(0)
	v_mfma_f32_16x16x32_bf16 v[112:115], v[128:131], v[182:185], v[112:115]
	v_mfma_f32_16x16x32_bf16 v[116:119], v[136:139], v[182:185], v[116:119]
	v_mfma_f32_16x16x32_bf16 v[80:83], v[128:131], v[224:227], v[80:83]
	v_mfma_f32_16x16x32_bf16 v[88:91], v[136:139], v[224:227], v[88:91]
	v_mfma_f32_16x16x32_bf16 v[64:67], v[128:131], v[232:235], v[64:67]
	v_mfma_f32_16x16x32_bf16 v[68:71], v[136:139], v[232:235], v[68:71]
	v_mfma_f32_16x16x32_bf16 v[48:51], v[128:131], v[240:243], v[48:51]
	v_mfma_f32_16x16x32_bf16 v[52:55], v[136:139], v[240:243], v[52:55]
	v_mfma_f32_16x16x32_bf16 v[112:115], v[132:135], v[218:221], v[112:115]
	v_mfma_f32_16x16x32_bf16 v[116:119], v[140:143], v[218:221], v[116:119]
	v_mfma_f32_16x16x32_bf16 v[80:83], v[132:135], v[228:231], v[80:83]
	v_mfma_f32_16x16x32_bf16 v[88:91], v[140:143], v[228:231], v[88:91]
	v_mfma_f32_16x16x32_bf16 v[64:67], v[132:135], v[236:239], v[64:67]
	v_mfma_f32_16x16x32_bf16 v[68:71], v[140:143], v[236:239], v[68:71]
	v_mfma_f32_16x16x32_bf16 v[48:51], v[132:135], v[244:247], v[48:51]
	v_mfma_f32_16x16x32_bf16 v[52:55], v[140:143], v[244:247], v[52:55]
	s_setprio 0
	s_setprio 1
	v_mfma_f32_16x16x32_bf16 v[120:123], v[144:147], v[182:185], v[120:123]
	v_mfma_f32_16x16x32_bf16 v[124:127], v[152:155], v[182:185], v[124:127]
	v_mfma_f32_16x16x32_bf16 v[96:99], v[144:147], v[224:227], v[96:99]
	v_mfma_f32_16x16x32_bf16 v[104:107], v[152:155], v[224:227], v[104:107]
	v_mfma_f32_16x16x32_bf16 v[72:75], v[144:147], v[232:235], v[72:75]
	v_mfma_f32_16x16x32_bf16 v[76:79], v[152:155], v[232:235], v[76:79]
	v_mfma_f32_16x16x32_bf16 v[56:59], v[144:147], v[240:243], v[56:59]
	v_mfma_f32_16x16x32_bf16 v[60:63], v[152:155], v[240:243], v[60:63]
	v_mfma_f32_16x16x32_bf16 v[120:123], v[148:151], v[218:221], v[120:123]
	v_mfma_f32_16x16x32_bf16 v[124:127], v[178:181], v[218:221], v[124:127]
	v_mfma_f32_16x16x32_bf16 v[96:99], v[148:151], v[228:231], v[96:99]
	v_mfma_f32_16x16x32_bf16 v[104:107], v[178:181], v[228:231], v[104:107]
	v_mfma_f32_16x16x32_bf16 v[72:75], v[148:151], v[236:239], v[72:75]
	v_mfma_f32_16x16x32_bf16 v[76:79], v[178:181], v[236:239], v[76:79]
	v_mfma_f32_16x16x32_bf16 v[56:59], v[148:151], v[244:247], v[56:59]
	v_mfma_f32_16x16x32_bf16 v[60:63], v[178:181], v[244:247], v[60:63]
	s_setprio 0
	s_barrier
	s_add_i32 s92, s70, s62
	v_lshl_add_u64 v[186:187], s[6:7], 0, v[158:159]
	s_mov_b32 m0, s92
	ds_read_b128 v[182:185], v206 offset:16384
	ds_read_b128 v[218:221], v206 offset:17408
	ds_read_b128 v[224:227], v206 offset:18432
	ds_read_b128 v[228:231], v206 offset:19456
	ds_read_b128 v[232:235], v206 offset:20480
	ds_read_b128 v[236:239], v206 offset:21504
	ds_read_b128 v[240:243], v206 offset:22528
	ds_read_b128 v[244:247], v206 offset:23552
	global_load_lds_dwordx4 v[186:187], off
	s_add_i32 m0, s92, 0x2000
	s_add_u32 s92, s6, 0x40000
	v_lshl_add_u64 v[248:249], s[6:7], 0, v[162:163]
	s_addc_u32 s93, s7, 0
	s_add_i32 s94, s71, s62
	global_load_lds_dwordx4 v[248:249], off
	v_lshl_add_u64 v[250:251], s[92:93], 0, v[158:159]
	s_mov_b32 m0, s94
	v_lshl_add_u64 v[252:253], s[12:13], 0, v[160:161]
	global_load_lds_dwordx4 v[250:251], off
	v_lshl_add_u64 v[250:251], s[92:93], 0, v[162:163]
	s_add_i32 m0, s94, 0x2000
	s_nop 0
	global_load_lds_dwordx4 v[250:251], off
	v_lshl_add_u64 v[250:251], s[12:13], 0, v[156:157]
	s_mov_b32 m0, s25
	s_nop 0
	global_load_lds_dwordx4 v[250:251], off
	s_mov_b32 m0, s63
	s_nop 0
	global_load_lds_dwordx4 v[252:253], off
	s_waitcnt vmcnt(8)
	s_waitcnt lgkmcnt(0)
	s_barrier
	s_setprio 1
	s_waitcnt lgkmcnt(0)
	v_mfma_f32_16x16x32_bf16 v[32:35], v[128:131], v[182:185], v[32:35]
	v_mfma_f32_16x16x32_bf16 v[36:39], v[136:139], v[182:185], v[36:39]
	v_mfma_f32_16x16x32_bf16 v[16:19], v[128:131], v[224:227], v[16:19]
	v_mfma_f32_16x16x32_bf16 v[20:23], v[136:139], v[224:227], v[20:23]
	v_mfma_f32_16x16x32_bf16 v[0:3], v[128:131], v[232:235], v[0:3]
	v_mfma_f32_16x16x32_bf16 v[4:7], v[136:139], v[232:235], v[4:7]
	v_mfma_f32_16x16x32_bf16 v[84:87], v[128:131], v[240:243], v[84:87]
	v_mfma_f32_16x16x32_bf16 v[92:95], v[136:139], v[240:243], v[92:95]
	v_mfma_f32_16x16x32_bf16 v[32:35], v[132:135], v[218:221], v[32:35]
	v_mfma_f32_16x16x32_bf16 v[36:39], v[140:143], v[218:221], v[36:39]
	v_mfma_f32_16x16x32_bf16 v[16:19], v[132:135], v[228:231], v[16:19]
	v_mfma_f32_16x16x32_bf16 v[20:23], v[140:143], v[228:231], v[20:23]
	v_mfma_f32_16x16x32_bf16 v[0:3], v[132:135], v[236:239], v[0:3]
	v_mfma_f32_16x16x32_bf16 v[4:7], v[140:143], v[236:239], v[4:7]
	v_mfma_f32_16x16x32_bf16 v[84:87], v[132:135], v[244:247], v[84:87]
	v_mfma_f32_16x16x32_bf16 v[92:95], v[140:143], v[244:247], v[92:95]
	s_setprio 0
	s_setprio 1
	v_mfma_f32_16x16x32_bf16 v[40:43], v[144:147], v[182:185], v[40:43]
	v_mfma_f32_16x16x32_bf16 v[44:47], v[152:155], v[182:185], v[44:47]
	v_mfma_f32_16x16x32_bf16 v[24:27], v[144:147], v[224:227], v[24:27]
	v_mfma_f32_16x16x32_bf16 v[28:31], v[152:155], v[224:227], v[28:31]
	v_mfma_f32_16x16x32_bf16 v[8:11], v[144:147], v[232:235], v[8:11]
	v_mfma_f32_16x16x32_bf16 v[12:15], v[152:155], v[232:235], v[12:15]
	v_mfma_f32_16x16x32_bf16 v[100:103], v[144:147], v[240:243], v[100:103]
	v_mfma_f32_16x16x32_bf16 v[108:111], v[152:155], v[240:243], v[108:111]
	v_mfma_f32_16x16x32_bf16 v[40:43], v[148:151], v[218:221], v[40:43]
	v_mfma_f32_16x16x32_bf16 v[44:47], v[178:181], v[218:221], v[44:47]
	v_mfma_f32_16x16x32_bf16 v[24:27], v[148:151], v[228:231], v[24:27]
	v_mfma_f32_16x16x32_bf16 v[28:31], v[178:181], v[228:231], v[28:31]
	v_mfma_f32_16x16x32_bf16 v[8:11], v[148:151], v[236:239], v[8:11]
	v_mfma_f32_16x16x32_bf16 v[12:15], v[178:181], v[236:239], v[12:15]
	v_mfma_f32_16x16x32_bf16 v[100:103], v[148:151], v[244:247], v[100:103]
	v_mfma_f32_16x16x32_bf16 v[108:111], v[178:181], v[244:247], v[108:111]
	s_setprio 0
	s_barrier
	s_add_i32 s92, 0, 0x18000
	s_add_i32 s93, 0, 0x1c000
	v_add_u32_e32 v140, s92, v188
	v_add_u32_e32 v164, s93, v188
	ds_read_b128 v[128:131], v140
	ds_read_b128 v[132:135], v140 offset:1024
	ds_read_b128 v[136:139], v140 offset:2048
	ds_read_b128 v[140:143], v140 offset:3072
	ds_read_b128 v[144:147], v164
	ds_read_b128 v[148:151], v164 offset:1024
	ds_read_b128 v[152:155], v164 offset:2048
	ds_read_b128 v[178:181], v164 offset:3072
	s_add_u32 s12, s12, 0x40000
	s_addc_u32 s13, s13, 0
	s_mov_b32 m0, s64
	v_lshl_add_u64 v[200:201], s[12:13], 0, v[156:157]
	ds_read_b128 v[182:185], v206 offset:32768
	ds_read_b128 v[218:221], v206 offset:33792
	ds_read_b128 v[224:227], v206 offset:34816
	ds_read_b128 v[228:231], v206 offset:35840
	ds_read_b128 v[232:235], v206 offset:36864
	ds_read_b128 v[236:239], v206 offset:37888
	ds_read_b128 v[240:243], v206 offset:38912
	ds_read_b128 v[244:247], v206 offset:39936
	global_load_lds_dwordx4 v[200:201], off
	v_lshl_add_u64 v[200:201], s[12:13], 0, v[160:161]
	s_mov_b32 m0, s65
	s_nop 0
	global_load_lds_dwordx4 v[200:201], off
	s_waitcnt vmcnt(8)
	s_waitcnt lgkmcnt(0)
	s_barrier
	s_setprio 1
	s_waitcnt lgkmcnt(0)
	v_mfma_f32_16x16x32_bf16 v[112:115], v[128:131], v[182:185], v[112:115]
	v_mfma_f32_16x16x32_bf16 v[116:119], v[136:139], v[182:185], v[116:119]
	v_mfma_f32_16x16x32_bf16 v[80:83], v[128:131], v[224:227], v[80:83]
	v_mfma_f32_16x16x32_bf16 v[88:91], v[136:139], v[224:227], v[88:91]
	v_mfma_f32_16x16x32_bf16 v[64:67], v[128:131], v[232:235], v[64:67]
	v_mfma_f32_16x16x32_bf16 v[68:71], v[136:139], v[232:235], v[68:71]
	v_mfma_f32_16x16x32_bf16 v[48:51], v[128:131], v[240:243], v[48:51]
	v_mfma_f32_16x16x32_bf16 v[52:55], v[136:139], v[240:243], v[52:55]
	v_mfma_f32_16x16x32_bf16 v[112:115], v[132:135], v[218:221], v[112:115]
	v_mfma_f32_16x16x32_bf16 v[116:119], v[140:143], v[218:221], v[116:119]
	v_mfma_f32_16x16x32_bf16 v[80:83], v[132:135], v[228:231], v[80:83]
	v_mfma_f32_16x16x32_bf16 v[88:91], v[140:143], v[228:231], v[88:91]
	v_mfma_f32_16x16x32_bf16 v[64:67], v[132:135], v[236:239], v[64:67]
	v_mfma_f32_16x16x32_bf16 v[68:71], v[140:143], v[236:239], v[68:71]
	v_mfma_f32_16x16x32_bf16 v[48:51], v[132:135], v[244:247], v[48:51]
	v_mfma_f32_16x16x32_bf16 v[52:55], v[140:143], v[244:247], v[52:55]
	s_setprio 0
	s_setprio 1
	v_mfma_f32_16x16x32_bf16 v[120:123], v[144:147], v[182:185], v[120:123]
	v_mfma_f32_16x16x32_bf16 v[124:127], v[152:155], v[182:185], v[124:127]
	v_mfma_f32_16x16x32_bf16 v[96:99], v[144:147], v[224:227], v[96:99]
	v_mfma_f32_16x16x32_bf16 v[104:107], v[152:155], v[224:227], v[104:107]
	v_mfma_f32_16x16x32_bf16 v[72:75], v[144:147], v[232:235], v[72:75]
	v_mfma_f32_16x16x32_bf16 v[76:79], v[152:155], v[232:235], v[76:79]
	v_mfma_f32_16x16x32_bf16 v[56:59], v[144:147], v[240:243], v[56:59]
	v_mfma_f32_16x16x32_bf16 v[60:63], v[152:155], v[240:243], v[60:63]
	v_mfma_f32_16x16x32_bf16 v[120:123], v[148:151], v[218:221], v[120:123]
	v_mfma_f32_16x16x32_bf16 v[124:127], v[178:181], v[218:221], v[124:127]
	v_mfma_f32_16x16x32_bf16 v[96:99], v[148:151], v[228:231], v[96:99]
	v_mfma_f32_16x16x32_bf16 v[104:107], v[178:181], v[228:231], v[104:107]
	v_mfma_f32_16x16x32_bf16 v[72:75], v[148:151], v[236:239], v[72:75]
	v_mfma_f32_16x16x32_bf16 v[76:79], v[178:181], v[236:239], v[76:79]
	v_mfma_f32_16x16x32_bf16 v[56:59], v[148:151], v[244:247], v[56:59]
	v_mfma_f32_16x16x32_bf16 v[60:63], v[178:181], v[244:247], v[60:63]
	s_setprio 0
	s_barrier
	s_add_i32 s12, s92, s62
	v_lshl_add_u64 v[186:187], v[186:187], 0, s[50:51]
	s_mov_b32 m0, s12
	ds_read_b128 v[182:185], v206 offset:49152
	ds_read_b128 v[218:221], v206 offset:50176
	ds_read_b128 v[224:227], v206 offset:51200
	ds_read_b128 v[228:231], v206 offset:52224
	ds_read_b128 v[232:235], v206 offset:53248
	ds_read_b128 v[236:239], v206 offset:54272
	ds_read_b128 v[240:243], v206 offset:55296
	ds_read_b128 v[244:247], v206 offset:56320
	global_load_lds_dwordx4 v[186:187], off
	s_add_i32 m0, s12, 0x2000
	s_add_u32 s6, s6, 0x40080
	v_lshl_add_u64 v[186:187], v[248:249], 0, s[50:51]
	s_addc_u32 s7, s7, 0
	s_add_i32 s12, s93, s62
	global_load_lds_dwordx4 v[186:187], off
	v_lshl_add_u64 v[186:187], s[6:7], 0, v[158:159]
	s_mov_b32 m0, s12
	s_nop 0
	global_load_lds_dwordx4 v[186:187], off
	v_lshl_add_u64 v[186:187], s[6:7], 0, v[162:163]
	s_add_i32 m0, s12, 0x2000
	s_nop 0
	global_load_lds_dwordx4 v[186:187], off
	v_lshl_add_u64 v[186:187], v[250:251], 0, s[50:51]
	s_mov_b32 m0, s78
	s_nop 0
	global_load_lds_dwordx4 v[186:187], off
	v_lshl_add_u64 v[186:187], v[252:253], 0, s[50:51]
	s_mov_b32 m0, s79
	s_nop 0
	global_load_lds_dwordx4 v[186:187], off
	s_add_i32 s91, s91, 2
	s_add_u32 s4, s4, 0x100
	s_addc_u32 s5, s5, 0
	s_add_u32 s85, s85, 0x100
	s_addc_u32 s90, s90, 0
	s_waitcnt vmcnt(8)
	s_waitcnt lgkmcnt(0)
	s_barrier
	s_setprio 1
	s_waitcnt lgkmcnt(0)
	v_mfma_f32_16x16x32_bf16 v[32:35], v[128:131], v[182:185], v[32:35]
	v_mfma_f32_16x16x32_bf16 v[36:39], v[136:139], v[182:185], v[36:39]
	v_mfma_f32_16x16x32_bf16 v[16:19], v[128:131], v[224:227], v[16:19]
	v_mfma_f32_16x16x32_bf16 v[20:23], v[136:139], v[224:227], v[20:23]
	v_mfma_f32_16x16x32_bf16 v[0:3], v[128:131], v[232:235], v[0:3]
	v_mfma_f32_16x16x32_bf16 v[4:7], v[136:139], v[232:235], v[4:7]
	v_mfma_f32_16x16x32_bf16 v[84:87], v[128:131], v[240:243], v[84:87]
	v_mfma_f32_16x16x32_bf16 v[92:95], v[136:139], v[240:243], v[92:95]
	v_mfma_f32_16x16x32_bf16 v[32:35], v[132:135], v[218:221], v[32:35]
	v_mfma_f32_16x16x32_bf16 v[36:39], v[140:143], v[218:221], v[36:39]
	v_mfma_f32_16x16x32_bf16 v[16:19], v[132:135], v[228:231], v[16:19]
	v_mfma_f32_16x16x32_bf16 v[20:23], v[140:143], v[228:231], v[20:23]
	v_mfma_f32_16x16x32_bf16 v[0:3], v[132:135], v[236:239], v[0:3]
	v_mfma_f32_16x16x32_bf16 v[4:7], v[140:143], v[236:239], v[4:7]
	v_mfma_f32_16x16x32_bf16 v[84:87], v[132:135], v[244:247], v[84:87]
	v_mfma_f32_16x16x32_bf16 v[92:95], v[140:143], v[244:247], v[92:95]
	s_setprio 0
	s_setprio 1
	v_mfma_f32_16x16x32_bf16 v[40:43], v[144:147], v[182:185], v[40:43]
	v_mfma_f32_16x16x32_bf16 v[44:47], v[152:155], v[182:185], v[44:47]
	v_mfma_f32_16x16x32_bf16 v[24:27], v[144:147], v[224:227], v[24:27]
	v_mfma_f32_16x16x32_bf16 v[28:31], v[152:155], v[224:227], v[28:31]
	v_mfma_f32_16x16x32_bf16 v[8:11], v[144:147], v[232:235], v[8:11]
	v_mfma_f32_16x16x32_bf16 v[12:15], v[152:155], v[232:235], v[12:15]
	v_mfma_f32_16x16x32_bf16 v[100:103], v[144:147], v[240:243], v[100:103]
	v_mfma_f32_16x16x32_bf16 v[108:111], v[152:155], v[240:243], v[108:111]
	v_mfma_f32_16x16x32_bf16 v[40:43], v[148:151], v[218:221], v[40:43]
	v_mfma_f32_16x16x32_bf16 v[44:47], v[178:181], v[218:221], v[44:47]
	v_mfma_f32_16x16x32_bf16 v[24:27], v[148:151], v[228:231], v[24:27]
	v_mfma_f32_16x16x32_bf16 v[28:31], v[178:181], v[228:231], v[28:31]
	v_mfma_f32_16x16x32_bf16 v[8:11], v[148:151], v[236:239], v[8:11]
	v_mfma_f32_16x16x32_bf16 v[12:15], v[178:181], v[236:239], v[12:15]
	v_mfma_f32_16x16x32_bf16 v[100:103], v[148:151], v[244:247], v[100:103]
	v_mfma_f32_16x16x32_bf16 v[108:111], v[178:181], v[244:247], v[108:111]
	s_setprio 0
	s_barrier
	s_cmp_gt_u32 s91, 13
	s_cbranch_scc0 .LBB0_476
	s_and_b64 vcc, exec, s[52:53]
	s_cbranch_vccz .LBB0_479
	s_barrier

.LBB0_1471:
	ds_read_b128 v[144:147], v159
	ds_read_b128 v[162:165], v159 offset:1024
	ds_read_b128 v[166:169], v159 offset:2048
	ds_read_b128 v[170:173], v159 offset:3072
	ds_read_b128 v[174:177], v160
	ds_read_b128 v[178:181], v160 offset:1024
	ds_read_b128 v[182:185], v160 offset:2048
	ds_read_b128 v[186:189], v160 offset:3072
	s_add_u32 s46, s44, 0xfffe0080
	s_addc_u32 s47, s45, -1
	s_cmp_eq_u32 s66, 4
	s_cselect_b32 s49, s10, s47
	s_cselect_b32 s48, s11, s46
	s_cselect_b32 s47, s19, s65
	s_cselect_b32 s46, s21, s64
	v_lshl_add_u64 v[224:225], s[44:45], 0, v[136:137]
	s_add_i32 m0, s43, 0xc000
	ds_read_b128 v[190:193], v161
	ds_read_b128 v[194:197], v161 offset:1024
	ds_read_b128 v[200:203], v161 offset:2048
	ds_read_b128 v[204:207], v161 offset:3072
	ds_read_b128 v[208:211], v161 offset:4096
	ds_read_b128 v[212:215], v161 offset:5120
	ds_read_b128 v[216:219], v161 offset:6144
	ds_read_b128 v[220:223], v161 offset:7168
	global_load_lds_dwordx4 v[224:225], off
	v_lshl_add_u64 v[224:225], s[44:45], 0, v[138:139]
	s_add_i32 m0, s43, 0xe000
	s_nop 0
	global_load_lds_dwordx4 v[224:225], off
	s_waitcnt vmcnt(8)
	s_waitcnt lgkmcnt(0)
	s_barrier
	s_setprio 1
	s_waitcnt lgkmcnt(0)
	v_mfma_f32_16x16x32_bf16 v[124:127], v[144:147], v[190:193], v[124:127]
	v_mfma_f32_16x16x32_bf16 v[120:123], v[166:169], v[190:193], v[120:123]
	v_mfma_f32_16x16x32_bf16 v[108:111], v[144:147], v[200:203], v[108:111]
	v_mfma_f32_16x16x32_bf16 v[104:107], v[166:169], v[200:203], v[104:107]
	v_mfma_f32_16x16x32_bf16 v[92:95], v[144:147], v[208:211], v[92:95]
	v_mfma_f32_16x16x32_bf16 v[88:91], v[166:169], v[208:211], v[88:91]
	v_mfma_f32_16x16x32_bf16 v[76:79], v[144:147], v[216:219], v[76:79]
	v_mfma_f32_16x16x32_bf16 v[72:75], v[166:169], v[216:219], v[72:75]
	v_mfma_f32_16x16x32_bf16 v[124:127], v[162:165], v[194:197], v[124:127]
	v_mfma_f32_16x16x32_bf16 v[120:123], v[170:173], v[194:197], v[120:123]
	v_mfma_f32_16x16x32_bf16 v[108:111], v[162:165], v[204:207], v[108:111]
	v_mfma_f32_16x16x32_bf16 v[104:107], v[170:173], v[204:207], v[104:107]
	v_mfma_f32_16x16x32_bf16 v[92:95], v[162:165], v[212:215], v[92:95]
	v_mfma_f32_16x16x32_bf16 v[88:91], v[170:173], v[212:215], v[88:91]
	v_mfma_f32_16x16x32_bf16 v[76:79], v[162:165], v[220:223], v[76:79]
	v_mfma_f32_16x16x32_bf16 v[72:75], v[170:173], v[220:223], v[72:75]
	s_setprio 0
	s_setprio 1
	v_mfma_f32_16x16x32_bf16 v[116:119], v[174:177], v[190:193], v[116:119]
	v_mfma_f32_16x16x32_bf16 v[112:115], v[182:185], v[190:193], v[112:115]
	v_mfma_f32_16x16x32_bf16 v[100:103], v[174:177], v[200:203], v[100:103]
	v_mfma_f32_16x16x32_bf16 v[96:99], v[182:185], v[200:203], v[96:99]
	v_mfma_f32_16x16x32_bf16 v[84:87], v[174:177], v[208:211], v[84:87]
	v_mfma_f32_16x16x32_bf16 v[80:83], v[182:185], v[208:211], v[80:83]
	v_mfma_f32_16x16x32_bf16 v[68:71], v[174:177], v[216:219], v[68:71]
	v_mfma_f32_16x16x32_bf16 v[64:67], v[182:185], v[216:219], v[64:67]
	v_mfma_f32_16x16x32_bf16 v[116:119], v[178:181], v[194:197], v[116:119]
	v_mfma_f32_16x16x32_bf16 v[112:115], v[186:189], v[194:197], v[112:115]
	v_mfma_f32_16x16x32_bf16 v[100:103], v[178:181], v[204:207], v[100:103]
	v_mfma_f32_16x16x32_bf16 v[96:99], v[186:189], v[204:207], v[96:99]
	v_mfma_f32_16x16x32_bf16 v[84:87], v[178:181], v[212:215], v[84:87]
	v_mfma_f32_16x16x32_bf16 v[80:83], v[186:189], v[212:215], v[80:83]
	v_mfma_f32_16x16x32_bf16 v[68:71], v[178:181], v[220:223], v[68:71]
	v_mfma_f32_16x16x32_bf16 v[64:67], v[186:189], v[220:223], v[64:67]
	s_setprio 0
	s_barrier
	s_add_i32 s67, s61, s52
	v_lshl_add_u64 v[224:225], s[46:47], 0, v[130:131]
	s_mov_b32 m0, s67
	ds_read_b128 v[190:193], v161 offset:16384
	ds_read_b128 v[194:197], v161 offset:17408
	ds_read_b128 v[200:203], v161 offset:18432
	ds_read_b128 v[204:207], v161 offset:19456
	ds_read_b128 v[208:211], v161 offset:20480
	ds_read_b128 v[212:215], v161 offset:21504
	ds_read_b128 v[216:219], v161 offset:22528
	ds_read_b128 v[220:223], v161 offset:23552
	global_load_lds_dwordx4 v[224:225], off
	s_add_i32 m0, s67, 0x2000
	s_add_u32 s70, s46, 0x20000
	v_lshl_add_u64 v[226:227], s[46:47], 0, v[134:135]
	s_addc_u32 s71, s47, 0
	s_add_i32 s67, s62, s52
	global_load_lds_dwordx4 v[226:227], off
	v_lshl_add_u64 v[228:229], s[70:71], 0, v[130:131]
	s_mov_b32 m0, s67
	v_lshl_add_u64 v[230:231], s[48:49], 0, v[132:133]
	global_load_lds_dwordx4 v[228:229], off
	v_lshl_add_u64 v[228:229], s[70:71], 0, v[134:135]
	s_add_i32 m0, s67, 0x2000
	s_nop 0
	global_load_lds_dwordx4 v[228:229], off
	v_lshl_add_u64 v[228:229], s[48:49], 0, v[128:129]
	s_mov_b32 m0, s43
	s_nop 0
	global_load_lds_dwordx4 v[228:229], off
	s_mov_b32 m0, s53
	s_nop 0
	global_load_lds_dwordx4 v[230:231], off
	s_waitcnt vmcnt(8)
	s_waitcnt lgkmcnt(0)
	s_barrier
	s_setprio 1
	s_waitcnt lgkmcnt(0)
	v_mfma_f32_16x16x32_bf16 v[60:63], v[144:147], v[190:193], v[60:63]
	v_mfma_f32_16x16x32_bf16 v[56:59], v[166:169], v[190:193], v[56:59]
	v_mfma_f32_16x16x32_bf16 v[44:47], v[144:147], v[200:203], v[44:47]
	v_mfma_f32_16x16x32_bf16 v[40:43], v[166:169], v[200:203], v[40:43]
	v_mfma_f32_16x16x32_bf16 v[28:31], v[144:147], v[208:211], v[28:31]
	v_mfma_f32_16x16x32_bf16 v[24:27], v[166:169], v[208:211], v[24:27]
	v_mfma_f32_16x16x32_bf16 v[12:15], v[144:147], v[216:219], v[12:15]
	v_mfma_f32_16x16x32_bf16 v[8:11], v[166:169], v[216:219], v[8:11]
	v_mfma_f32_16x16x32_bf16 v[60:63], v[162:165], v[194:197], v[60:63]
	v_mfma_f32_16x16x32_bf16 v[56:59], v[170:173], v[194:197], v[56:59]
	v_mfma_f32_16x16x32_bf16 v[44:47], v[162:165], v[204:207], v[44:47]
	v_mfma_f32_16x16x32_bf16 v[40:43], v[170:173], v[204:207], v[40:43]
	v_mfma_f32_16x16x32_bf16 v[28:31], v[162:165], v[212:215], v[28:31]
	v_mfma_f32_16x16x32_bf16 v[24:27], v[170:173], v[212:215], v[24:27]
	v_mfma_f32_16x16x32_bf16 v[12:15], v[162:165], v[220:223], v[12:15]
	v_mfma_f32_16x16x32_bf16 v[8:11], v[170:173], v[220:223], v[8:11]
	s_setprio 0
	s_setprio 1
	v_mfma_f32_16x16x32_bf16 v[52:55], v[174:177], v[190:193], v[52:55]
	v_mfma_f32_16x16x32_bf16 v[48:51], v[182:185], v[190:193], v[48:51]
	v_mfma_f32_16x16x32_bf16 v[36:39], v[174:177], v[200:203], v[36:39]
	v_mfma_f32_16x16x32_bf16 v[32:35], v[182:185], v[200:203], v[32:35]
	v_mfma_f32_16x16x32_bf16 v[20:23], v[174:177], v[208:211], v[20:23]
	v_mfma_f32_16x16x32_bf16 v[16:19], v[182:185], v[208:211], v[16:19]
	v_mfma_f32_16x16x32_bf16 v[4:7], v[174:177], v[216:219], v[4:7]
	v_mfma_f32_16x16x32_bf16 v[0:3], v[182:185], v[216:219], v[0:3]
	v_mfma_f32_16x16x32_bf16 v[52:55], v[178:181], v[194:197], v[52:55]
	v_mfma_f32_16x16x32_bf16 v[48:51], v[186:189], v[194:197], v[48:51]
	v_mfma_f32_16x16x32_bf16 v[36:39], v[178:181], v[204:207], v[36:39]
	v_mfma_f32_16x16x32_bf16 v[32:35], v[186:189], v[204:207], v[32:35]
	v_mfma_f32_16x16x32_bf16 v[20:23], v[178:181], v[212:215], v[20:23]
	v_mfma_f32_16x16x32_bf16 v[16:19], v[186:189], v[212:215], v[16:19]
	v_mfma_f32_16x16x32_bf16 v[4:7], v[178:181], v[220:223], v[4:7]
	v_mfma_f32_16x16x32_bf16 v[0:3], v[186:189], v[220:223], v[0:3]
	s_setprio 0
	s_barrier
	s_add_i32 s67, 0, 0x18000
	s_add_i32 s70, 0, 0x1c000
	v_add_u32_e32 v170, s67, v157
	v_add_u32_e32 v186, s70, v157
	ds_read_b128 v[144:147], v170
	ds_read_b128 v[162:165], v170 offset:1024
	ds_read_b128 v[166:169], v170 offset:2048
	ds_read_b128 v[170:173], v170 offset:3072
	ds_read_b128 v[174:177], v186
	ds_read_b128 v[178:181], v186 offset:1024
	ds_read_b128 v[182:185], v186 offset:2048
	ds_read_b128 v[186:189], v186 offset:3072
	s_add_u32 s48, s48, 0x20000
	s_addc_u32 s49, s49, 0
	s_mov_b32 m0, s54
	v_lshl_add_u64 v[232:233], s[48:49], 0, v[128:129]
	ds_read_b128 v[190:193], v161 offset:32768
	ds_read_b128 v[194:197], v161 offset:33792
	ds_read_b128 v[200:203], v161 offset:34816
	ds_read_b128 v[204:207], v161 offset:35840
	ds_read_b128 v[208:211], v161 offset:36864
	ds_read_b128 v[212:215], v161 offset:37888
	ds_read_b128 v[216:219], v161 offset:38912
	ds_read_b128 v[220:223], v161 offset:39936
	global_load_lds_dwordx4 v[232:233], off
	v_lshl_add_u64 v[232:233], s[48:49], 0, v[132:133]
	s_mov_b32 m0, s55
	s_nop 0
	global_load_lds_dwordx4 v[232:233], off
	s_waitcnt vmcnt(8)
	s_waitcnt lgkmcnt(0)
	s_barrier
	s_setprio 1
	s_waitcnt lgkmcnt(0)
	v_mfma_f32_16x16x32_bf16 v[124:127], v[144:147], v[190:193], v[124:127]
	v_mfma_f32_16x16x32_bf16 v[120:123], v[166:169], v[190:193], v[120:123]
	v_mfma_f32_16x16x32_bf16 v[108:111], v[144:147], v[200:203], v[108:111]
	v_mfma_f32_16x16x32_bf16 v[104:107], v[166:169], v[200:203], v[104:107]
	v_mfma_f32_16x16x32_bf16 v[92:95], v[144:147], v[208:211], v[92:95]
	v_mfma_f32_16x16x32_bf16 v[88:91], v[166:169], v[208:211], v[88:91]
	v_mfma_f32_16x16x32_bf16 v[76:79], v[144:147], v[216:219], v[76:79]
	v_mfma_f32_16x16x32_bf16 v[72:75], v[166:169], v[216:219], v[72:75]
	v_mfma_f32_16x16x32_bf16 v[124:127], v[162:165], v[194:197], v[124:127]
	v_mfma_f32_16x16x32_bf16 v[120:123], v[170:173], v[194:197], v[120:123]
	v_mfma_f32_16x16x32_bf16 v[108:111], v[162:165], v[204:207], v[108:111]
	v_mfma_f32_16x16x32_bf16 v[104:107], v[170:173], v[204:207], v[104:107]
	v_mfma_f32_16x16x32_bf16 v[92:95], v[162:165], v[212:215], v[92:95]
	v_mfma_f32_16x16x32_bf16 v[88:91], v[170:173], v[212:215], v[88:91]
	v_mfma_f32_16x16x32_bf16 v[76:79], v[162:165], v[220:223], v[76:79]
	v_mfma_f32_16x16x32_bf16 v[72:75], v[170:173], v[220:223], v[72:75]
	s_setprio 0
	s_setprio 1
	v_mfma_f32_16x16x32_bf16 v[116:119], v[174:177], v[190:193], v[116:119]
	v_mfma_f32_16x16x32_bf16 v[112:115], v[182:185], v[190:193], v[112:115]
	v_mfma_f32_16x16x32_bf16 v[100:103], v[174:177], v[200:203], v[100:103]
	v_mfma_f32_16x16x32_bf16 v[96:99], v[182:185], v[200:203], v[96:99]
	v_mfma_f32_16x16x32_bf16 v[84:87], v[174:177], v[208:211], v[84:87]
	v_mfma_f32_16x16x32_bf16 v[80:83], v[182:185], v[208:211], v[80:83]
	v_mfma_f32_16x16x32_bf16 v[68:71], v[174:177], v[216:219], v[68:71]
	v_mfma_f32_16x16x32_bf16 v[64:67], v[182:185], v[216:219], v[64:67]
	v_mfma_f32_16x16x32_bf16 v[116:119], v[178:181], v[194:197], v[116:119]
	v_mfma_f32_16x16x32_bf16 v[112:115], v[186:189], v[194:197], v[112:115]
	v_mfma_f32_16x16x32_bf16 v[100:103], v[178:181], v[204:207], v[100:103]
	v_mfma_f32_16x16x32_bf16 v[96:99], v[186:189], v[204:207], v[96:99]
	v_mfma_f32_16x16x32_bf16 v[84:87], v[178:181], v[212:215], v[84:87]
	v_mfma_f32_16x16x32_bf16 v[80:83], v[186:189], v[212:215], v[80:83]
	v_mfma_f32_16x16x32_bf16 v[68:71], v[178:181], v[220:223], v[68:71]
	v_mfma_f32_16x16x32_bf16 v[64:67], v[186:189], v[220:223], v[64:67]
	s_setprio 0
	s_barrier
	s_add_i32 s48, s67, s52
	v_lshl_add_u64 v[224:225], v[224:225], 0, s[8:9]
	s_mov_b32 m0, s48
	ds_read_b128 v[190:193], v161 offset:49152
	ds_read_b128 v[194:197], v161 offset:50176
	ds_read_b128 v[200:203], v161 offset:51200
	ds_read_b128 v[204:207], v161 offset:52224
	ds_read_b128 v[208:211], v161 offset:53248
	ds_read_b128 v[212:215], v161 offset:54272
	ds_read_b128 v[216:219], v161 offset:55296
	ds_read_b128 v[220:223], v161 offset:56320
	global_load_lds_dwordx4 v[224:225], off
	s_add_i32 m0, s48, 0x2000
	s_add_u32 s46, s46, 0x20080
	v_lshl_add_u64 v[224:225], v[226:227], 0, s[8:9]
	s_addc_u32 s47, s47, 0
	s_add_i32 s48, s70, s52
	global_load_lds_dwordx4 v[224:225], off
	v_lshl_add_u64 v[224:225], s[46:47], 0, v[130:131]
	s_mov_b32 m0, s48
	s_nop 0
	global_load_lds_dwordx4 v[224:225], off
	v_lshl_add_u64 v[224:225], s[46:47], 0, v[134:135]
	s_add_i32 m0, s48, 0x2000
	s_nop 0
	global_load_lds_dwordx4 v[224:225], off
	v_lshl_add_u64 v[224:225], v[228:229], 0, s[8:9]
	s_mov_b32 m0, s57
	s_nop 0
	global_load_lds_dwordx4 v[224:225], off
	v_lshl_add_u64 v[224:225], v[230:231], 0, s[8:9]
	s_mov_b32 m0, s58
	s_nop 0
	global_load_lds_dwordx4 v[224:225], off
	s_add_i32 s66, s66, 2
	s_add_u32 s44, s44, 0x100
	s_addc_u32 s45, s45, 0
	s_add_u32 s64, s64, 0x100
	s_addc_u32 s65, s65, 0
	s_waitcnt vmcnt(8)
	s_waitcnt lgkmcnt(0)
	s_barrier
	s_setprio 1
	s_waitcnt lgkmcnt(0)
	v_mfma_f32_16x16x32_bf16 v[60:63], v[144:147], v[190:193], v[60:63]
	v_mfma_f32_16x16x32_bf16 v[56:59], v[166:169], v[190:193], v[56:59]
	v_mfma_f32_16x16x32_bf16 v[44:47], v[144:147], v[200:203], v[44:47]
	v_mfma_f32_16x16x32_bf16 v[40:43], v[166:169], v[200:203], v[40:43]
	v_mfma_f32_16x16x32_bf16 v[28:31], v[144:147], v[208:211], v[28:31]
	v_mfma_f32_16x16x32_bf16 v[24:27], v[166:169], v[208:211], v[24:27]
	v_mfma_f32_16x16x32_bf16 v[12:15], v[144:147], v[216:219], v[12:15]
	v_mfma_f32_16x16x32_bf16 v[8:11], v[166:169], v[216:219], v[8:11]
	v_mfma_f32_16x16x32_bf16 v[60:63], v[162:165], v[194:197], v[60:63]
	v_mfma_f32_16x16x32_bf16 v[56:59], v[170:173], v[194:197], v[56:59]
	v_mfma_f32_16x16x32_bf16 v[44:47], v[162:165], v[204:207], v[44:47]
	v_mfma_f32_16x16x32_bf16 v[40:43], v[170:173], v[204:207], v[40:43]
	v_mfma_f32_16x16x32_bf16 v[28:31], v[162:165], v[212:215], v[28:31]
	v_mfma_f32_16x16x32_bf16 v[24:27], v[170:173], v[212:215], v[24:27]
	v_mfma_f32_16x16x32_bf16 v[12:15], v[162:165], v[220:223], v[12:15]
	v_mfma_f32_16x16x32_bf16 v[8:11], v[170:173], v[220:223], v[8:11]
	s_setprio 0
	s_setprio 1
	v_mfma_f32_16x16x32_bf16 v[52:55], v[174:177], v[190:193], v[52:55]
	v_mfma_f32_16x16x32_bf16 v[48:51], v[182:185], v[190:193], v[48:51]
	v_mfma_f32_16x16x32_bf16 v[36:39], v[174:177], v[200:203], v[36:39]
	v_mfma_f32_16x16x32_bf16 v[32:35], v[182:185], v[200:203], v[32:35]
	v_mfma_f32_16x16x32_bf16 v[20:23], v[174:177], v[208:211], v[20:23]
	v_mfma_f32_16x16x32_bf16 v[16:19], v[182:185], v[208:211], v[16:19]
	v_mfma_f32_16x16x32_bf16 v[4:7], v[174:177], v[216:219], v[4:7]
	v_mfma_f32_16x16x32_bf16 v[0:3], v[182:185], v[216:219], v[0:3]
	v_mfma_f32_16x16x32_bf16 v[52:55], v[178:181], v[194:197], v[52:55]
	v_mfma_f32_16x16x32_bf16 v[48:51], v[186:189], v[194:197], v[48:51]
	v_mfma_f32_16x16x32_bf16 v[36:39], v[178:181], v[204:207], v[36:39]
	v_mfma_f32_16x16x32_bf16 v[32:35], v[186:189], v[204:207], v[32:35]
	v_mfma_f32_16x16x32_bf16 v[20:23], v[178:181], v[212:215], v[20:23]
	v_mfma_f32_16x16x32_bf16 v[16:19], v[186:189], v[212:215], v[16:19]
	v_mfma_f32_16x16x32_bf16 v[4:7], v[178:181], v[220:223], v[4:7]
	v_mfma_f32_16x16x32_bf16 v[0:3], v[186:189], v[220:223], v[0:3]
	s_setprio 0
	s_barrier
	s_cmp_gt_u32 s66, 5
	s_cbranch_scc0 .LBB0_1471
	s_and_b64 vcc, exec, s[12:13]
	s_cbranch_vccz .LBB0_1474
	s_barrier

.LBB0_1495:
	ds_read_b128 v[144:147], v153
	ds_read_b128 v[156:159], v153 offset:1024
	ds_read_b128 v[160:163], v153 offset:2048
	ds_read_b128 v[164:167], v153 offset:3072
	ds_read_b128 v[168:171], v154
	ds_read_b128 v[172:175], v154 offset:1024
	ds_read_b128 v[176:179], v154 offset:2048
	ds_read_b128 v[180:183], v154 offset:3072
	s_add_u32 s48, s46, 0xfffe0080
	s_addc_u32 s49, s47, -1
	s_cmp_eq_u32 s66, 4
	s_cselect_b32 s51, s10, s49
	s_cselect_b32 s50, s11, s48
	s_cselect_b32 s49, s21, s65
	s_cselect_b32 s48, s25, s64
	v_lshl_add_u64 v[148:149], s[46:47], 0, v[136:137]
	s_add_i32 m0, s45, 0xc000
	ds_read_b128 v[184:187], v155
	ds_read_b128 v[188:191], v155 offset:1024
	ds_read_b128 v[192:195], v155 offset:2048
	ds_read_b128 v[200:203], v155 offset:3072
	ds_read_b128 v[204:207], v155 offset:4096
	ds_read_b128 v[208:211], v155 offset:5120
	ds_read_b128 v[212:215], v155 offset:6144
	ds_read_b128 v[216:219], v155 offset:7168
	global_load_lds_dwordx4 v[148:149], off
	v_lshl_add_u64 v[148:149], s[46:47], 0, v[138:139]
	s_add_i32 m0, s45, 0xe000
	s_nop 0
	global_load_lds_dwordx4 v[148:149], off
	s_waitcnt vmcnt(8)
	s_waitcnt lgkmcnt(0)
	s_barrier
	s_setprio 1
	s_waitcnt lgkmcnt(0)
	v_mfma_f32_16x16x32_bf16 v[124:127], v[144:147], v[184:187], v[124:127]
	v_mfma_f32_16x16x32_bf16 v[120:123], v[160:163], v[184:187], v[120:123]
	v_mfma_f32_16x16x32_bf16 v[108:111], v[144:147], v[192:195], v[108:111]
	v_mfma_f32_16x16x32_bf16 v[104:107], v[160:163], v[192:195], v[104:107]
	v_mfma_f32_16x16x32_bf16 v[92:95], v[144:147], v[204:207], v[92:95]
	v_mfma_f32_16x16x32_bf16 v[88:91], v[160:163], v[204:207], v[88:91]
	v_mfma_f32_16x16x32_bf16 v[76:79], v[144:147], v[212:215], v[76:79]
	v_mfma_f32_16x16x32_bf16 v[72:75], v[160:163], v[212:215], v[72:75]
	v_mfma_f32_16x16x32_bf16 v[124:127], v[156:159], v[188:191], v[124:127]
	v_mfma_f32_16x16x32_bf16 v[120:123], v[164:167], v[188:191], v[120:123]
	v_mfma_f32_16x16x32_bf16 v[108:111], v[156:159], v[200:203], v[108:111]
	v_mfma_f32_16x16x32_bf16 v[104:107], v[164:167], v[200:203], v[104:107]
	v_mfma_f32_16x16x32_bf16 v[92:95], v[156:159], v[208:211], v[92:95]
	v_mfma_f32_16x16x32_bf16 v[88:91], v[164:167], v[208:211], v[88:91]
	v_mfma_f32_16x16x32_bf16 v[76:79], v[156:159], v[216:219], v[76:79]
	v_mfma_f32_16x16x32_bf16 v[72:75], v[164:167], v[216:219], v[72:75]
	s_setprio 0
	s_setprio 1
	v_mfma_f32_16x16x32_bf16 v[116:119], v[168:171], v[184:187], v[116:119]
	v_mfma_f32_16x16x32_bf16 v[112:115], v[176:179], v[184:187], v[112:115]
	v_mfma_f32_16x16x32_bf16 v[100:103], v[168:171], v[192:195], v[100:103]
	v_mfma_f32_16x16x32_bf16 v[96:99], v[176:179], v[192:195], v[96:99]
	v_mfma_f32_16x16x32_bf16 v[84:87], v[168:171], v[204:207], v[84:87]
	v_mfma_f32_16x16x32_bf16 v[80:83], v[176:179], v[204:207], v[80:83]
	v_mfma_f32_16x16x32_bf16 v[68:71], v[168:171], v[212:215], v[68:71]
	v_mfma_f32_16x16x32_bf16 v[64:67], v[176:179], v[212:215], v[64:67]
	v_mfma_f32_16x16x32_bf16 v[116:119], v[172:175], v[188:191], v[116:119]
	v_mfma_f32_16x16x32_bf16 v[112:115], v[180:183], v[188:191], v[112:115]
	v_mfma_f32_16x16x32_bf16 v[100:103], v[172:175], v[200:203], v[100:103]
	v_mfma_f32_16x16x32_bf16 v[96:99], v[180:183], v[200:203], v[96:99]
	v_mfma_f32_16x16x32_bf16 v[84:87], v[172:175], v[208:211], v[84:87]
	v_mfma_f32_16x16x32_bf16 v[80:83], v[180:183], v[208:211], v[80:83]
	v_mfma_f32_16x16x32_bf16 v[68:71], v[172:175], v[216:219], v[68:71]
	v_mfma_f32_16x16x32_bf16 v[64:67], v[180:183], v[216:219], v[64:67]
	s_setprio 0
	s_barrier
	s_add_i32 s67, s61, s52
	v_lshl_add_u64 v[148:149], s[48:49], 0, v[130:131]
	s_mov_b32 m0, s67
	ds_read_b128 v[184:187], v155 offset:16384
	ds_read_b128 v[188:191], v155 offset:17408
	ds_read_b128 v[192:195], v155 offset:18432
	ds_read_b128 v[200:203], v155 offset:19456
	ds_read_b128 v[204:207], v155 offset:20480
	ds_read_b128 v[208:211], v155 offset:21504
	ds_read_b128 v[212:215], v155 offset:22528
	ds_read_b128 v[216:219], v155 offset:23552
	global_load_lds_dwordx4 v[148:149], off
	s_add_i32 m0, s67, 0x2000
	s_add_u32 s70, s48, 0x20000
	v_lshl_add_u64 v[196:197], s[48:49], 0, v[134:135]
	s_addc_u32 s71, s49, 0
	s_add_i32 s67, s62, s52
	global_load_lds_dwordx4 v[196:197], off
	v_lshl_add_u64 v[220:221], s[70:71], 0, v[130:131]
	s_mov_b32 m0, s67
	v_lshl_add_u64 v[222:223], s[50:51], 0, v[132:133]
	global_load_lds_dwordx4 v[220:221], off
	v_lshl_add_u64 v[220:221], s[70:71], 0, v[134:135]
	s_add_i32 m0, s67, 0x2000
	s_nop 0
	global_load_lds_dwordx4 v[220:221], off
	v_lshl_add_u64 v[220:221], s[50:51], 0, v[128:129]
	s_mov_b32 m0, s45
	s_nop 0
	global_load_lds_dwordx4 v[220:221], off
	s_mov_b32 m0, s53
	s_nop 0
	global_load_lds_dwordx4 v[222:223], off
	s_waitcnt vmcnt(8)
	s_waitcnt lgkmcnt(0)
	s_barrier
	s_setprio 1
	s_waitcnt lgkmcnt(0)
	v_mfma_f32_16x16x32_bf16 v[60:63], v[144:147], v[184:187], v[60:63]
	v_mfma_f32_16x16x32_bf16 v[56:59], v[160:163], v[184:187], v[56:59]
	v_mfma_f32_16x16x32_bf16 v[44:47], v[144:147], v[192:195], v[44:47]
	v_mfma_f32_16x16x32_bf16 v[40:43], v[160:163], v[192:195], v[40:43]
	v_mfma_f32_16x16x32_bf16 v[28:31], v[144:147], v[204:207], v[28:31]
	v_mfma_f32_16x16x32_bf16 v[24:27], v[160:163], v[204:207], v[24:27]
	v_mfma_f32_16x16x32_bf16 v[12:15], v[144:147], v[212:215], v[12:15]
	v_mfma_f32_16x16x32_bf16 v[8:11], v[160:163], v[212:215], v[8:11]
	v_mfma_f32_16x16x32_bf16 v[60:63], v[156:159], v[188:191], v[60:63]
	v_mfma_f32_16x16x32_bf16 v[56:59], v[164:167], v[188:191], v[56:59]
	v_mfma_f32_16x16x32_bf16 v[44:47], v[156:159], v[200:203], v[44:47]
	v_mfma_f32_16x16x32_bf16 v[40:43], v[164:167], v[200:203], v[40:43]
	v_mfma_f32_16x16x32_bf16 v[28:31], v[156:159], v[208:211], v[28:31]
	v_mfma_f32_16x16x32_bf16 v[24:27], v[164:167], v[208:211], v[24:27]
	v_mfma_f32_16x16x32_bf16 v[12:15], v[156:159], v[216:219], v[12:15]
	v_mfma_f32_16x16x32_bf16 v[8:11], v[164:167], v[216:219], v[8:11]
	s_setprio 0
	s_setprio 1
	v_mfma_f32_16x16x32_bf16 v[52:55], v[168:171], v[184:187], v[52:55]
	v_mfma_f32_16x16x32_bf16 v[48:51], v[176:179], v[184:187], v[48:51]
	v_mfma_f32_16x16x32_bf16 v[36:39], v[168:171], v[192:195], v[36:39]
	v_mfma_f32_16x16x32_bf16 v[32:35], v[176:179], v[192:195], v[32:35]
	v_mfma_f32_16x16x32_bf16 v[20:23], v[168:171], v[204:207], v[20:23]
	v_mfma_f32_16x16x32_bf16 v[16:19], v[176:179], v[204:207], v[16:19]
	v_mfma_f32_16x16x32_bf16 v[4:7], v[168:171], v[212:215], v[4:7]
	v_mfma_f32_16x16x32_bf16 v[0:3], v[176:179], v[212:215], v[0:3]
	v_mfma_f32_16x16x32_bf16 v[52:55], v[172:175], v[188:191], v[52:55]
	v_mfma_f32_16x16x32_bf16 v[48:51], v[180:183], v[188:191], v[48:51]
	v_mfma_f32_16x16x32_bf16 v[36:39], v[172:175], v[200:203], v[36:39]
	v_mfma_f32_16x16x32_bf16 v[32:35], v[180:183], v[200:203], v[32:35]
	v_mfma_f32_16x16x32_bf16 v[20:23], v[172:175], v[208:211], v[20:23]
	v_mfma_f32_16x16x32_bf16 v[16:19], v[180:183], v[208:211], v[16:19]
	v_mfma_f32_16x16x32_bf16 v[4:7], v[172:175], v[216:219], v[4:7]
	v_mfma_f32_16x16x32_bf16 v[0:3], v[180:183], v[216:219], v[0:3]
	s_setprio 0
	s_barrier
	s_add_i32 s67, 0, 0x18000
	s_add_i32 s70, 0, 0x1c000
	v_add_u32_e32 v164, s67, v151
	v_add_u32_e32 v180, s70, v151
	ds_read_b128 v[144:147], v164
	ds_read_b128 v[156:159], v164 offset:1024
	ds_read_b128 v[160:163], v164 offset:2048
	ds_read_b128 v[164:167], v164 offset:3072
	ds_read_b128 v[168:171], v180
	ds_read_b128 v[172:175], v180 offset:1024
	ds_read_b128 v[176:179], v180 offset:2048
	ds_read_b128 v[180:183], v180 offset:3072
	s_add_u32 s50, s50, 0x20000
	s_addc_u32 s51, s51, 0
	s_mov_b32 m0, s54
	v_lshl_add_u64 v[224:225], s[50:51], 0, v[128:129]
	ds_read_b128 v[184:187], v155 offset:32768
	ds_read_b128 v[188:191], v155 offset:33792
	ds_read_b128 v[192:195], v155 offset:34816
	ds_read_b128 v[200:203], v155 offset:35840
	ds_read_b128 v[204:207], v155 offset:36864
	ds_read_b128 v[208:211], v155 offset:37888
	ds_read_b128 v[212:215], v155 offset:38912
	ds_read_b128 v[216:219], v155 offset:39936
	global_load_lds_dwordx4 v[224:225], off
	v_lshl_add_u64 v[224:225], s[50:51], 0, v[132:133]
	s_mov_b32 m0, s55
	s_nop 0
	global_load_lds_dwordx4 v[224:225], off
	s_waitcnt vmcnt(8)
	s_waitcnt lgkmcnt(0)
	s_barrier
	s_setprio 1
	s_waitcnt lgkmcnt(0)
	v_mfma_f32_16x16x32_bf16 v[124:127], v[144:147], v[184:187], v[124:127]
	v_mfma_f32_16x16x32_bf16 v[120:123], v[160:163], v[184:187], v[120:123]
	v_mfma_f32_16x16x32_bf16 v[108:111], v[144:147], v[192:195], v[108:111]
	v_mfma_f32_16x16x32_bf16 v[104:107], v[160:163], v[192:195], v[104:107]
	v_mfma_f32_16x16x32_bf16 v[92:95], v[144:147], v[204:207], v[92:95]
	v_mfma_f32_16x16x32_bf16 v[88:91], v[160:163], v[204:207], v[88:91]
	v_mfma_f32_16x16x32_bf16 v[76:79], v[144:147], v[212:215], v[76:79]
	v_mfma_f32_16x16x32_bf16 v[72:75], v[160:163], v[212:215], v[72:75]
	v_mfma_f32_16x16x32_bf16 v[124:127], v[156:159], v[188:191], v[124:127]
	v_mfma_f32_16x16x32_bf16 v[120:123], v[164:167], v[188:191], v[120:123]
	v_mfma_f32_16x16x32_bf16 v[108:111], v[156:159], v[200:203], v[108:111]
	v_mfma_f32_16x16x32_bf16 v[104:107], v[164:167], v[200:203], v[104:107]
	v_mfma_f32_16x16x32_bf16 v[92:95], v[156:159], v[208:211], v[92:95]
	v_mfma_f32_16x16x32_bf16 v[88:91], v[164:167], v[208:211], v[88:91]
	v_mfma_f32_16x16x32_bf16 v[76:79], v[156:159], v[216:219], v[76:79]
	v_mfma_f32_16x16x32_bf16 v[72:75], v[164:167], v[216:219], v[72:75]
	s_setprio 0
	s_setprio 1
	v_mfma_f32_16x16x32_bf16 v[116:119], v[168:171], v[184:187], v[116:119]
	v_mfma_f32_16x16x32_bf16 v[112:115], v[176:179], v[184:187], v[112:115]
	v_mfma_f32_16x16x32_bf16 v[100:103], v[168:171], v[192:195], v[100:103]
	v_mfma_f32_16x16x32_bf16 v[96:99], v[176:179], v[192:195], v[96:99]
	v_mfma_f32_16x16x32_bf16 v[84:87], v[168:171], v[204:207], v[84:87]
	v_mfma_f32_16x16x32_bf16 v[80:83], v[176:179], v[204:207], v[80:83]
	v_mfma_f32_16x16x32_bf16 v[68:71], v[168:171], v[212:215], v[68:71]
	v_mfma_f32_16x16x32_bf16 v[64:67], v[176:179], v[212:215], v[64:67]
	v_mfma_f32_16x16x32_bf16 v[116:119], v[172:175], v[188:191], v[116:119]
	v_mfma_f32_16x16x32_bf16 v[112:115], v[180:183], v[188:191], v[112:115]
	v_mfma_f32_16x16x32_bf16 v[100:103], v[172:175], v[200:203], v[100:103]
	v_mfma_f32_16x16x32_bf16 v[96:99], v[180:183], v[200:203], v[96:99]
	v_mfma_f32_16x16x32_bf16 v[84:87], v[172:175], v[208:211], v[84:87]
	v_mfma_f32_16x16x32_bf16 v[80:83], v[180:183], v[208:211], v[80:83]
	v_mfma_f32_16x16x32_bf16 v[68:71], v[172:175], v[216:219], v[68:71]
	v_mfma_f32_16x16x32_bf16 v[64:67], v[180:183], v[216:219], v[64:67]
	s_setprio 0
	s_barrier
	s_add_i32 s50, s67, s52
	v_lshl_add_u64 v[148:149], v[148:149], 0, s[6:7]
	s_mov_b32 m0, s50
	ds_read_b128 v[184:187], v155 offset:49152
	ds_read_b128 v[188:191], v155 offset:50176
	ds_read_b128 v[192:195], v155 offset:51200
	ds_read_b128 v[200:203], v155 offset:52224
	ds_read_b128 v[204:207], v155 offset:53248
	ds_read_b128 v[208:211], v155 offset:54272
	ds_read_b128 v[212:215], v155 offset:55296
	ds_read_b128 v[216:219], v155 offset:56320
	global_load_lds_dwordx4 v[148:149], off
	s_add_i32 m0, s50, 0x2000
	s_add_u32 s48, s48, 0x20080
	v_lshl_add_u64 v[148:149], v[196:197], 0, s[6:7]
	s_addc_u32 s49, s49, 0
	s_add_i32 s50, s70, s52
	global_load_lds_dwordx4 v[148:149], off
	v_lshl_add_u64 v[148:149], s[48:49], 0, v[130:131]
	s_mov_b32 m0, s50
	s_nop 0
	global_load_lds_dwordx4 v[148:149], off
	v_lshl_add_u64 v[148:149], s[48:49], 0, v[134:135]
	s_add_i32 m0, s50, 0x2000
	s_nop 0
	global_load_lds_dwordx4 v[148:149], off
	v_lshl_add_u64 v[148:149], v[220:221], 0, s[6:7]
	s_mov_b32 m0, s57
	s_nop 0
	global_load_lds_dwordx4 v[148:149], off
	v_lshl_add_u64 v[148:149], v[222:223], 0, s[6:7]
	s_mov_b32 m0, s58
	s_nop 0
	global_load_lds_dwordx4 v[148:149], off
	s_add_i32 s66, s66, 2
	s_add_u32 s46, s46, 0x100
	s_addc_u32 s47, s47, 0
	s_add_u32 s64, s64, 0x100
	s_addc_u32 s65, s65, 0
	s_waitcnt vmcnt(8)
	s_waitcnt lgkmcnt(0)
	s_barrier
	s_setprio 1
	s_waitcnt lgkmcnt(0)
	v_mfma_f32_16x16x32_bf16 v[60:63], v[144:147], v[184:187], v[60:63]
	v_mfma_f32_16x16x32_bf16 v[56:59], v[160:163], v[184:187], v[56:59]
	v_mfma_f32_16x16x32_bf16 v[44:47], v[144:147], v[192:195], v[44:47]
	v_mfma_f32_16x16x32_bf16 v[40:43], v[160:163], v[192:195], v[40:43]
	v_mfma_f32_16x16x32_bf16 v[28:31], v[144:147], v[204:207], v[28:31]
	v_mfma_f32_16x16x32_bf16 v[24:27], v[160:163], v[204:207], v[24:27]
	v_mfma_f32_16x16x32_bf16 v[12:15], v[144:147], v[212:215], v[12:15]
	v_mfma_f32_16x16x32_bf16 v[8:11], v[160:163], v[212:215], v[8:11]
	v_mfma_f32_16x16x32_bf16 v[60:63], v[156:159], v[188:191], v[60:63]
	v_mfma_f32_16x16x32_bf16 v[56:59], v[164:167], v[188:191], v[56:59]
	v_mfma_f32_16x16x32_bf16 v[44:47], v[156:159], v[200:203], v[44:47]
	v_mfma_f32_16x16x32_bf16 v[40:43], v[164:167], v[200:203], v[40:43]
	v_mfma_f32_16x16x32_bf16 v[28:31], v[156:159], v[208:211], v[28:31]
	v_mfma_f32_16x16x32_bf16 v[24:27], v[164:167], v[208:211], v[24:27]
	v_mfma_f32_16x16x32_bf16 v[12:15], v[156:159], v[216:219], v[12:15]
	v_mfma_f32_16x16x32_bf16 v[8:11], v[164:167], v[216:219], v[8:11]
	s_setprio 0
	s_setprio 1
	v_mfma_f32_16x16x32_bf16 v[52:55], v[168:171], v[184:187], v[52:55]
	v_mfma_f32_16x16x32_bf16 v[48:51], v[176:179], v[184:187], v[48:51]
	v_mfma_f32_16x16x32_bf16 v[36:39], v[168:171], v[192:195], v[36:39]
	v_mfma_f32_16x16x32_bf16 v[32:35], v[176:179], v[192:195], v[32:35]
	v_mfma_f32_16x16x32_bf16 v[20:23], v[168:171], v[204:207], v[20:23]
	v_mfma_f32_16x16x32_bf16 v[16:19], v[176:179], v[204:207], v[16:19]
	v_mfma_f32_16x16x32_bf16 v[4:7], v[168:171], v[212:215], v[4:7]
	v_mfma_f32_16x16x32_bf16 v[0:3], v[176:179], v[212:215], v[0:3]
	v_mfma_f32_16x16x32_bf16 v[52:55], v[172:175], v[188:191], v[52:55]
	v_mfma_f32_16x16x32_bf16 v[48:51], v[180:183], v[188:191], v[48:51]
	v_mfma_f32_16x16x32_bf16 v[36:39], v[172:175], v[200:203], v[36:39]
	v_mfma_f32_16x16x32_bf16 v[32:35], v[180:183], v[200:203], v[32:35]
	v_mfma_f32_16x16x32_bf16 v[20:23], v[172:175], v[208:211], v[20:23]
	v_mfma_f32_16x16x32_bf16 v[16:19], v[180:183], v[208:211], v[16:19]
	v_mfma_f32_16x16x32_bf16 v[4:7], v[172:175], v[216:219], v[4:7]
	v_mfma_f32_16x16x32_bf16 v[0:3], v[180:183], v[216:219], v[0:3]
	s_setprio 0
	s_barrier
	s_cmp_gt_u32 s66, 5
	s_cbranch_scc0 .LBB0_1495
	s_and_b64 vcc, exec, s[8:9]
	s_cbranch_vccz .LBB0_1498
	s_barrier

.LBB0_1576:
	ds_read_b128 v[88:91], v175
	ds_read_b128 v[92:95], v175 offset:1024
	ds_read_b128 v[96:99], v175 offset:2048
	ds_read_b128 v[100:103], v175 offset:3072
	ds_read_b128 v[160:163], v176
	ds_read_b128 v[164:167], v176 offset:1024
	ds_read_b128 v[168:171], v176 offset:2048
	ds_read_b128 v[180:183], v176 offset:3072
	s_add_u32 s50, s48, 0xfffc0080
	s_addc_u32 s51, s49, -1
	s_cmp_eq_u32 s76, 12
	s_cselect_b32 s53, s10, s51
	s_cselect_b32 s52, s11, s50
	s_cselect_b32 s51, s21, s75
	s_cselect_b32 s50, s25, s45
	v_lshl_add_u64 v[196:197], s[48:49], 0, v[152:153]
	s_add_i32 m0, s47, 0xc000
	ds_read_b128 v[184:187], v177
	ds_read_b128 v[188:191], v177 offset:1024
	ds_read_b128 v[192:195], v177 offset:2048
	ds_read_b128 v[200:203], v177 offset:3072
	ds_read_b128 v[204:207], v177 offset:4096
	ds_read_b128 v[208:211], v177 offset:5120
	ds_read_b128 v[212:215], v177 offset:6144
	ds_read_b128 v[216:219], v177 offset:7168
	global_load_lds_dwordx4 v[196:197], off
	v_lshl_add_u64 v[196:197], s[48:49], 0, v[154:155]
	s_add_i32 m0, s47, 0xe000
	s_nop 0
	global_load_lds_dwordx4 v[196:197], off
	s_waitcnt vmcnt(8)
	s_waitcnt lgkmcnt(0)
	s_barrier
	s_setprio 1
	s_waitcnt lgkmcnt(0)
	v_mfma_f32_16x16x32_bf16 v[140:143], v[88:91], v[184:187], v[140:143]
	v_mfma_f32_16x16x32_bf16 v[136:139], v[96:99], v[184:187], v[136:139]
	v_mfma_f32_16x16x32_bf16 v[124:127], v[88:91], v[192:195], v[124:127]
	v_mfma_f32_16x16x32_bf16 v[120:123], v[96:99], v[192:195], v[120:123]
	v_mfma_f32_16x16x32_bf16 v[108:111], v[88:91], v[204:207], v[108:111]
	v_mfma_f32_16x16x32_bf16 v[104:107], v[96:99], v[204:207], v[104:107]
	v_mfma_f32_16x16x32_bf16 v[76:79], v[88:91], v[212:215], v[76:79]
	v_mfma_f32_16x16x32_bf16 v[72:75], v[96:99], v[212:215], v[72:75]
	v_mfma_f32_16x16x32_bf16 v[140:143], v[92:95], v[188:191], v[140:143]
	v_mfma_f32_16x16x32_bf16 v[136:139], v[100:103], v[188:191], v[136:139]
	v_mfma_f32_16x16x32_bf16 v[124:127], v[92:95], v[200:203], v[124:127]
	v_mfma_f32_16x16x32_bf16 v[120:123], v[100:103], v[200:203], v[120:123]
	v_mfma_f32_16x16x32_bf16 v[108:111], v[92:95], v[208:211], v[108:111]
	v_mfma_f32_16x16x32_bf16 v[104:107], v[100:103], v[208:211], v[104:107]
	v_mfma_f32_16x16x32_bf16 v[76:79], v[92:95], v[216:219], v[76:79]
	v_mfma_f32_16x16x32_bf16 v[72:75], v[100:103], v[216:219], v[72:75]
	s_setprio 0
	s_setprio 1
	v_mfma_f32_16x16x32_bf16 v[132:135], v[160:163], v[184:187], v[132:135]
	v_mfma_f32_16x16x32_bf16 v[128:131], v[168:171], v[184:187], v[128:131]
	v_mfma_f32_16x16x32_bf16 v[116:119], v[160:163], v[192:195], v[116:119]
	v_mfma_f32_16x16x32_bf16 v[112:115], v[168:171], v[192:195], v[112:115]
	v_mfma_f32_16x16x32_bf16 v[84:87], v[160:163], v[204:207], v[84:87]
	v_mfma_f32_16x16x32_bf16 v[80:83], v[168:171], v[204:207], v[80:83]
	v_mfma_f32_16x16x32_bf16 v[68:71], v[160:163], v[212:215], v[68:71]
	v_mfma_f32_16x16x32_bf16 v[64:67], v[168:171], v[212:215], v[64:67]
	v_mfma_f32_16x16x32_bf16 v[132:135], v[164:167], v[188:191], v[132:135]
	v_mfma_f32_16x16x32_bf16 v[128:131], v[180:183], v[188:191], v[128:131]
	v_mfma_f32_16x16x32_bf16 v[116:119], v[164:167], v[200:203], v[116:119]
	v_mfma_f32_16x16x32_bf16 v[112:115], v[180:183], v[200:203], v[112:115]
	v_mfma_f32_16x16x32_bf16 v[84:87], v[164:167], v[208:211], v[84:87]
	v_mfma_f32_16x16x32_bf16 v[80:83], v[180:183], v[208:211], v[80:83]
	v_mfma_f32_16x16x32_bf16 v[68:71], v[164:167], v[216:219], v[68:71]
	v_mfma_f32_16x16x32_bf16 v[64:67], v[180:183], v[216:219], v[64:67]
	s_setprio 0
	s_barrier
	s_add_i32 s77, s67, s55
	v_lshl_add_u64 v[196:197], s[50:51], 0, v[146:147]
	s_mov_b32 m0, s77
	ds_read_b128 v[184:187], v177 offset:16384
	ds_read_b128 v[188:191], v177 offset:17408
	ds_read_b128 v[192:195], v177 offset:18432
	ds_read_b128 v[200:203], v177 offset:19456
	ds_read_b128 v[204:207], v177 offset:20480
	ds_read_b128 v[208:211], v177 offset:21504
	ds_read_b128 v[212:215], v177 offset:22528
	ds_read_b128 v[216:219], v177 offset:23552
	global_load_lds_dwordx4 v[196:197], off
	s_add_i32 m0, s77, 0x2000
	s_add_u32 s78, s50, 0x40000
	v_lshl_add_u64 v[220:221], s[50:51], 0, v[150:151]
	s_addc_u32 s79, s51, 0
	s_add_i32 s77, s70, s55
	global_load_lds_dwordx4 v[220:221], off
	v_lshl_add_u64 v[222:223], s[78:79], 0, v[146:147]
	s_mov_b32 m0, s77
	v_lshl_add_u64 v[224:225], s[52:53], 0, v[148:149]
	global_load_lds_dwordx4 v[222:223], off
	v_lshl_add_u64 v[222:223], s[78:79], 0, v[150:151]
	s_add_i32 m0, s77, 0x2000
	s_nop 0
	global_load_lds_dwordx4 v[222:223], off
	v_lshl_add_u64 v[222:223], s[52:53], 0, v[144:145]
	s_mov_b32 m0, s47
	s_nop 0
	global_load_lds_dwordx4 v[222:223], off
	s_mov_b32 m0, s56
	s_nop 0
	global_load_lds_dwordx4 v[224:225], off
	s_waitcnt vmcnt(8)
	s_waitcnt lgkmcnt(0)
	s_barrier
	s_setprio 1
	s_waitcnt lgkmcnt(0)
	v_mfma_f32_16x16x32_bf16 v[60:63], v[88:91], v[184:187], v[60:63]
	v_mfma_f32_16x16x32_bf16 v[56:59], v[96:99], v[184:187], v[56:59]
	v_mfma_f32_16x16x32_bf16 v[44:47], v[88:91], v[192:195], v[44:47]
	v_mfma_f32_16x16x32_bf16 v[40:43], v[96:99], v[192:195], v[40:43]
	v_mfma_f32_16x16x32_bf16 v[28:31], v[88:91], v[204:207], v[28:31]
	v_mfma_f32_16x16x32_bf16 v[24:27], v[96:99], v[204:207], v[24:27]
	v_mfma_f32_16x16x32_bf16 v[12:15], v[88:91], v[212:215], v[12:15]
	v_mfma_f32_16x16x32_bf16 v[8:11], v[96:99], v[212:215], v[8:11]
	v_mfma_f32_16x16x32_bf16 v[60:63], v[92:95], v[188:191], v[60:63]
	v_mfma_f32_16x16x32_bf16 v[56:59], v[100:103], v[188:191], v[56:59]
	v_mfma_f32_16x16x32_bf16 v[44:47], v[92:95], v[200:203], v[44:47]
	v_mfma_f32_16x16x32_bf16 v[40:43], v[100:103], v[200:203], v[40:43]
	v_mfma_f32_16x16x32_bf16 v[28:31], v[92:95], v[208:211], v[28:31]
	v_mfma_f32_16x16x32_bf16 v[24:27], v[100:103], v[208:211], v[24:27]
	v_mfma_f32_16x16x32_bf16 v[12:15], v[92:95], v[216:219], v[12:15]
	v_mfma_f32_16x16x32_bf16 v[8:11], v[100:103], v[216:219], v[8:11]
	s_setprio 0
	s_setprio 1
	v_mfma_f32_16x16x32_bf16 v[52:55], v[160:163], v[184:187], v[52:55]
	v_mfma_f32_16x16x32_bf16 v[48:51], v[168:171], v[184:187], v[48:51]
	v_mfma_f32_16x16x32_bf16 v[36:39], v[160:163], v[192:195], v[36:39]
	v_mfma_f32_16x16x32_bf16 v[32:35], v[168:171], v[192:195], v[32:35]
	v_mfma_f32_16x16x32_bf16 v[20:23], v[160:163], v[204:207], v[20:23]
	v_mfma_f32_16x16x32_bf16 v[16:19], v[168:171], v[204:207], v[16:19]
	v_mfma_f32_16x16x32_bf16 v[4:7], v[160:163], v[212:215], v[4:7]
	v_mfma_f32_16x16x32_bf16 v[0:3], v[168:171], v[212:215], v[0:3]
	v_mfma_f32_16x16x32_bf16 v[52:55], v[164:167], v[188:191], v[52:55]
	v_mfma_f32_16x16x32_bf16 v[48:51], v[180:183], v[188:191], v[48:51]
	v_mfma_f32_16x16x32_bf16 v[36:39], v[164:167], v[200:203], v[36:39]
	v_mfma_f32_16x16x32_bf16 v[32:35], v[180:183], v[200:203], v[32:35]
	v_mfma_f32_16x16x32_bf16 v[20:23], v[164:167], v[208:211], v[20:23]
	v_mfma_f32_16x16x32_bf16 v[16:19], v[180:183], v[208:211], v[16:19]
	v_mfma_f32_16x16x32_bf16 v[4:7], v[164:167], v[216:219], v[4:7]
	v_mfma_f32_16x16x32_bf16 v[0:3], v[180:183], v[216:219], v[0:3]
	s_setprio 0
	s_barrier
	s_add_i32 s77, 0, 0x18000
	s_add_i32 s78, 0, 0x1c000
	v_add_u32_e32 v100, s77, v173
	v_add_u32_e32 v179, s78, v173
	ds_read_b128 v[88:91], v100
	ds_read_b128 v[92:95], v100 offset:1024
	ds_read_b128 v[96:99], v100 offset:2048
	ds_read_b128 v[100:103], v100 offset:3072
	ds_read_b128 v[160:163], v179
	ds_read_b128 v[164:167], v179 offset:1024
	ds_read_b128 v[168:171], v179 offset:2048
	ds_read_b128 v[180:183], v179 offset:3072
	s_add_u32 s52, s52, 0x40000
	s_addc_u32 s53, s53, 0
	s_mov_b32 m0, s57
	v_lshl_add_u64 v[226:227], s[52:53], 0, v[144:145]
	ds_read_b128 v[184:187], v177 offset:32768
	ds_read_b128 v[188:191], v177 offset:33792
	ds_read_b128 v[192:195], v177 offset:34816
	ds_read_b128 v[200:203], v177 offset:35840
	ds_read_b128 v[204:207], v177 offset:36864
	ds_read_b128 v[208:211], v177 offset:37888
	ds_read_b128 v[212:215], v177 offset:38912
	ds_read_b128 v[216:219], v177 offset:39936
	global_load_lds_dwordx4 v[226:227], off
	v_lshl_add_u64 v[226:227], s[52:53], 0, v[148:149]
	s_mov_b32 m0, s58
	s_nop 0
	global_load_lds_dwordx4 v[226:227], off
	s_waitcnt vmcnt(8)
	s_waitcnt lgkmcnt(0)
	s_barrier
	s_setprio 1
	s_waitcnt lgkmcnt(0)
	v_mfma_f32_16x16x32_bf16 v[140:143], v[88:91], v[184:187], v[140:143]
	v_mfma_f32_16x16x32_bf16 v[136:139], v[96:99], v[184:187], v[136:139]
	v_mfma_f32_16x16x32_bf16 v[124:127], v[88:91], v[192:195], v[124:127]
	v_mfma_f32_16x16x32_bf16 v[120:123], v[96:99], v[192:195], v[120:123]
	v_mfma_f32_16x16x32_bf16 v[108:111], v[88:91], v[204:207], v[108:111]
	v_mfma_f32_16x16x32_bf16 v[104:107], v[96:99], v[204:207], v[104:107]
	v_mfma_f32_16x16x32_bf16 v[76:79], v[88:91], v[212:215], v[76:79]
	v_mfma_f32_16x16x32_bf16 v[72:75], v[96:99], v[212:215], v[72:75]
	v_mfma_f32_16x16x32_bf16 v[140:143], v[92:95], v[188:191], v[140:143]
	v_mfma_f32_16x16x32_bf16 v[136:139], v[100:103], v[188:191], v[136:139]
	v_mfma_f32_16x16x32_bf16 v[124:127], v[92:95], v[200:203], v[124:127]
	v_mfma_f32_16x16x32_bf16 v[120:123], v[100:103], v[200:203], v[120:123]
	v_mfma_f32_16x16x32_bf16 v[108:111], v[92:95], v[208:211], v[108:111]
	v_mfma_f32_16x16x32_bf16 v[104:107], v[100:103], v[208:211], v[104:107]
	v_mfma_f32_16x16x32_bf16 v[76:79], v[92:95], v[216:219], v[76:79]
	v_mfma_f32_16x16x32_bf16 v[72:75], v[100:103], v[216:219], v[72:75]
	s_setprio 0
	s_setprio 1
	v_mfma_f32_16x16x32_bf16 v[132:135], v[160:163], v[184:187], v[132:135]
	v_mfma_f32_16x16x32_bf16 v[128:131], v[168:171], v[184:187], v[128:131]
	v_mfma_f32_16x16x32_bf16 v[116:119], v[160:163], v[192:195], v[116:119]
	v_mfma_f32_16x16x32_bf16 v[112:115], v[168:171], v[192:195], v[112:115]
	v_mfma_f32_16x16x32_bf16 v[84:87], v[160:163], v[204:207], v[84:87]
	v_mfma_f32_16x16x32_bf16 v[80:83], v[168:171], v[204:207], v[80:83]
	v_mfma_f32_16x16x32_bf16 v[68:71], v[160:163], v[212:215], v[68:71]
	v_mfma_f32_16x16x32_bf16 v[64:67], v[168:171], v[212:215], v[64:67]
	v_mfma_f32_16x16x32_bf16 v[132:135], v[164:167], v[188:191], v[132:135]
	v_mfma_f32_16x16x32_bf16 v[128:131], v[180:183], v[188:191], v[128:131]
	v_mfma_f32_16x16x32_bf16 v[116:119], v[164:167], v[200:203], v[116:119]
	v_mfma_f32_16x16x32_bf16 v[112:115], v[180:183], v[200:203], v[112:115]
	v_mfma_f32_16x16x32_bf16 v[84:87], v[164:167], v[208:211], v[84:87]
	v_mfma_f32_16x16x32_bf16 v[80:83], v[180:183], v[208:211], v[80:83]
	v_mfma_f32_16x16x32_bf16 v[68:71], v[164:167], v[216:219], v[68:71]
	v_mfma_f32_16x16x32_bf16 v[64:67], v[180:183], v[216:219], v[64:67]
	s_setprio 0
	s_barrier
	s_add_i32 s52, s77, s55
	v_lshl_add_u64 v[196:197], v[196:197], 0, s[8:9]
	s_mov_b32 m0, s52
	ds_read_b128 v[184:187], v177 offset:49152
	ds_read_b128 v[188:191], v177 offset:50176
	ds_read_b128 v[192:195], v177 offset:51200
	ds_read_b128 v[200:203], v177 offset:52224
	ds_read_b128 v[204:207], v177 offset:53248
	ds_read_b128 v[208:211], v177 offset:54272
	ds_read_b128 v[212:215], v177 offset:55296
	ds_read_b128 v[216:219], v177 offset:56320
	global_load_lds_dwordx4 v[196:197], off
	s_add_i32 m0, s52, 0x2000
	s_add_u32 s50, s50, 0x40080
	v_lshl_add_u64 v[196:197], v[220:221], 0, s[8:9]
	s_addc_u32 s51, s51, 0
	s_add_i32 s52, s78, s55
	global_load_lds_dwordx4 v[196:197], off
	v_lshl_add_u64 v[196:197], s[50:51], 0, v[146:147]
	s_mov_b32 m0, s52
	s_nop 0
	global_load_lds_dwordx4 v[196:197], off
	v_lshl_add_u64 v[196:197], s[50:51], 0, v[150:151]
	s_add_i32 m0, s52, 0x2000
	s_nop 0
	global_load_lds_dwordx4 v[196:197], off
	v_lshl_add_u64 v[196:197], v[222:223], 0, s[8:9]
	s_mov_b32 m0, s61
	s_nop 0
	global_load_lds_dwordx4 v[196:197], off
	v_lshl_add_u64 v[196:197], v[224:225], 0, s[8:9]
	s_mov_b32 m0, s62
	s_nop 0
	global_load_lds_dwordx4 v[196:197], off
	s_add_i32 s76, s76, 2
	s_add_u32 s48, s48, 0x100
	s_addc_u32 s49, s49, 0
	s_add_u32 s45, s45, 0x100
	s_addc_u32 s75, s75, 0
	s_waitcnt vmcnt(8)
	s_waitcnt lgkmcnt(0)
	s_barrier
	s_setprio 1
	s_waitcnt lgkmcnt(0)
	v_mfma_f32_16x16x32_bf16 v[60:63], v[88:91], v[184:187], v[60:63]
	v_mfma_f32_16x16x32_bf16 v[56:59], v[96:99], v[184:187], v[56:59]
	v_mfma_f32_16x16x32_bf16 v[44:47], v[88:91], v[192:195], v[44:47]
	v_mfma_f32_16x16x32_bf16 v[40:43], v[96:99], v[192:195], v[40:43]
	v_mfma_f32_16x16x32_bf16 v[28:31], v[88:91], v[204:207], v[28:31]
	v_mfma_f32_16x16x32_bf16 v[24:27], v[96:99], v[204:207], v[24:27]
	v_mfma_f32_16x16x32_bf16 v[12:15], v[88:91], v[212:215], v[12:15]
	v_mfma_f32_16x16x32_bf16 v[8:11], v[96:99], v[212:215], v[8:11]
	v_mfma_f32_16x16x32_bf16 v[60:63], v[92:95], v[188:191], v[60:63]
	v_mfma_f32_16x16x32_bf16 v[56:59], v[100:103], v[188:191], v[56:59]
	v_mfma_f32_16x16x32_bf16 v[44:47], v[92:95], v[200:203], v[44:47]
	v_mfma_f32_16x16x32_bf16 v[40:43], v[100:103], v[200:203], v[40:43]
	v_mfma_f32_16x16x32_bf16 v[28:31], v[92:95], v[208:211], v[28:31]
	v_mfma_f32_16x16x32_bf16 v[24:27], v[100:103], v[208:211], v[24:27]
	v_mfma_f32_16x16x32_bf16 v[12:15], v[92:95], v[216:219], v[12:15]
	v_mfma_f32_16x16x32_bf16 v[8:11], v[100:103], v[216:219], v[8:11]
	s_setprio 0
	s_setprio 1
	v_mfma_f32_16x16x32_bf16 v[52:55], v[160:163], v[184:187], v[52:55]
	v_mfma_f32_16x16x32_bf16 v[48:51], v[168:171], v[184:187], v[48:51]
	v_mfma_f32_16x16x32_bf16 v[36:39], v[160:163], v[192:195], v[36:39]
	v_mfma_f32_16x16x32_bf16 v[32:35], v[168:171], v[192:195], v[32:35]
	v_mfma_f32_16x16x32_bf16 v[20:23], v[160:163], v[204:207], v[20:23]
	v_mfma_f32_16x16x32_bf16 v[16:19], v[168:171], v[204:207], v[16:19]
	v_mfma_f32_16x16x32_bf16 v[4:7], v[160:163], v[212:215], v[4:7]
	v_mfma_f32_16x16x32_bf16 v[0:3], v[168:171], v[212:215], v[0:3]
	v_mfma_f32_16x16x32_bf16 v[52:55], v[164:167], v[188:191], v[52:55]
	v_mfma_f32_16x16x32_bf16 v[48:51], v[180:183], v[188:191], v[48:51]
	v_mfma_f32_16x16x32_bf16 v[36:39], v[164:167], v[200:203], v[36:39]
	v_mfma_f32_16x16x32_bf16 v[32:35], v[180:183], v[200:203], v[32:35]
	v_mfma_f32_16x16x32_bf16 v[20:23], v[164:167], v[208:211], v[20:23]
	v_mfma_f32_16x16x32_bf16 v[16:19], v[180:183], v[208:211], v[16:19]
	v_mfma_f32_16x16x32_bf16 v[4:7], v[164:167], v[216:219], v[4:7]
	v_mfma_f32_16x16x32_bf16 v[0:3], v[180:183], v[216:219], v[0:3]
	s_setprio 0
	s_barrier
	s_cmp_gt_u32 s76, 13
	s_cbranch_scc0 .LBB0_1576
	s_and_b64 vcc, exec, s[12:13]
	s_cbranch_vccz .LBB0_1579
	s_barrier

.LBB0_1671:
	ds_read_b128 v[64:67], v176
	ds_read_b128 v[68:71], v176 offset:1024
	ds_read_b128 v[76:79], v176 offset:2048
	ds_read_b128 v[80:83], v176 offset:3072
	ds_read_b128 v[184:187], v177
	ds_read_b128 v[188:191], v177 offset:1024
	ds_read_b128 v[192:195], v177 offset:2048
	ds_read_b128 v[200:203], v177 offset:3072
	s_add_u32 s26, s24, 0xfffc0080
	s_addc_u32 s27, s25, -1
	s_cmp_eq_u32 s66, 12
	s_cselect_b32 s43, s1, s27
	s_cselect_b32 s42, s10, s26
	s_cselect_b32 s27, s11, s65
	s_cselect_b32 s26, s17, s19
	v_lshl_add_u64 v[162:163], s[24:25], 0, v[154:155]
	s_add_i32 m0, s49, 0xc000
	ds_read_b128 v[204:207], v178
	ds_read_b128 v[208:211], v178 offset:1024
	ds_read_b128 v[212:215], v178 offset:2048
	ds_read_b128 v[216:219], v178 offset:3072
	ds_read_b128 v[220:223], v178 offset:4096
	ds_read_b128 v[224:227], v178 offset:5120
	ds_read_b128 v[228:231], v178 offset:6144
	ds_read_b128 v[232:235], v178 offset:7168
	global_load_lds_dwordx4 v[162:163], off
	v_lshl_add_u64 v[162:163], s[24:25], 0, v[156:157]
	s_add_i32 m0, s49, 0xe000
	s_nop 0
	global_load_lds_dwordx4 v[162:163], off
	s_waitcnt vmcnt(8)
	s_waitcnt lgkmcnt(0)
	s_barrier
	s_setprio 1
	s_waitcnt lgkmcnt(0)
	v_mfma_f32_16x16x32_bf16 v[140:143], v[64:67], v[204:207], v[140:143]
	v_mfma_f32_16x16x32_bf16 v[132:135], v[76:79], v[204:207], v[132:135]
	v_mfma_f32_16x16x32_bf16 v[124:127], v[64:67], v[212:215], v[124:127]
	v_mfma_f32_16x16x32_bf16 v[120:123], v[76:79], v[212:215], v[120:123]
	v_mfma_f32_16x16x32_bf16 v[108:111], v[64:67], v[220:223], v[108:111]
	v_mfma_f32_16x16x32_bf16 v[104:107], v[76:79], v[220:223], v[104:107]
	v_mfma_f32_16x16x32_bf16 v[92:95], v[64:67], v[228:231], v[92:95]
	v_mfma_f32_16x16x32_bf16 v[88:91], v[76:79], v[228:231], v[88:91]
	v_mfma_f32_16x16x32_bf16 v[140:143], v[68:71], v[208:211], v[140:143]
	v_mfma_f32_16x16x32_bf16 v[132:135], v[80:83], v[208:211], v[132:135]
	v_mfma_f32_16x16x32_bf16 v[124:127], v[68:71], v[216:219], v[124:127]
	v_mfma_f32_16x16x32_bf16 v[120:123], v[80:83], v[216:219], v[120:123]
	v_mfma_f32_16x16x32_bf16 v[108:111], v[68:71], v[224:227], v[108:111]
	v_mfma_f32_16x16x32_bf16 v[104:107], v[80:83], v[224:227], v[104:107]
	v_mfma_f32_16x16x32_bf16 v[92:95], v[68:71], v[232:235], v[92:95]
	v_mfma_f32_16x16x32_bf16 v[88:91], v[80:83], v[232:235], v[88:91]
	s_setprio 0
	s_setprio 1
	v_mfma_f32_16x16x32_bf16 v[136:139], v[184:187], v[204:207], v[136:139]
	v_mfma_f32_16x16x32_bf16 v[128:131], v[192:195], v[204:207], v[128:131]
	v_mfma_f32_16x16x32_bf16 v[116:119], v[184:187], v[212:215], v[116:119]
	v_mfma_f32_16x16x32_bf16 v[112:115], v[192:195], v[212:215], v[112:115]
	v_mfma_f32_16x16x32_bf16 v[100:103], v[184:187], v[220:223], v[100:103]
	v_mfma_f32_16x16x32_bf16 v[96:99], v[192:195], v[220:223], v[96:99]
	v_mfma_f32_16x16x32_bf16 v[84:87], v[184:187], v[228:231], v[84:87]
	v_mfma_f32_16x16x32_bf16 v[72:75], v[192:195], v[228:231], v[72:75]
	v_mfma_f32_16x16x32_bf16 v[136:139], v[188:191], v[208:211], v[136:139]
	v_mfma_f32_16x16x32_bf16 v[128:131], v[200:203], v[208:211], v[128:131]
	v_mfma_f32_16x16x32_bf16 v[116:119], v[188:191], v[216:219], v[116:119]
	v_mfma_f32_16x16x32_bf16 v[112:115], v[200:203], v[216:219], v[112:115]
	v_mfma_f32_16x16x32_bf16 v[100:103], v[188:191], v[224:227], v[100:103]
	v_mfma_f32_16x16x32_bf16 v[96:99], v[200:203], v[224:227], v[96:99]
	v_mfma_f32_16x16x32_bf16 v[84:87], v[188:191], v[232:235], v[84:87]
	v_mfma_f32_16x16x32_bf16 v[72:75], v[200:203], v[232:235], v[72:75]
	s_setprio 0
	s_barrier
	s_add_i32 s67, s58, s48
	v_lshl_add_u64 v[162:163], s[26:27], 0, v[146:147]
	s_mov_b32 m0, s67
	ds_read_b128 v[204:207], v178 offset:16384
	ds_read_b128 v[208:211], v178 offset:17408
	ds_read_b128 v[212:215], v178 offset:18432
	ds_read_b128 v[216:219], v178 offset:19456
	ds_read_b128 v[220:223], v178 offset:20480
	ds_read_b128 v[224:227], v178 offset:21504
	ds_read_b128 v[228:231], v178 offset:22528
	ds_read_b128 v[232:235], v178 offset:23552
	global_load_lds_dwordx4 v[162:163], off
	s_add_i32 m0, s67, 0x2000
	s_add_u32 s70, s26, 0x40000
	v_lshl_add_u64 v[196:197], s[26:27], 0, v[150:151]
	s_addc_u32 s71, s27, 0
	s_add_i32 s67, s59, s48
	global_load_lds_dwordx4 v[196:197], off
	v_lshl_add_u64 v[236:237], s[70:71], 0, v[146:147]
	s_mov_b32 m0, s67
	v_lshl_add_u64 v[238:239], s[42:43], 0, v[148:149]
	global_load_lds_dwordx4 v[236:237], off
	v_lshl_add_u64 v[236:237], s[70:71], 0, v[150:151]
	s_add_i32 m0, s67, 0x2000
	s_nop 0
	global_load_lds_dwordx4 v[236:237], off
	v_lshl_add_u64 v[236:237], s[42:43], 0, v[144:145]
	s_mov_b32 m0, s49
	s_nop 0
	global_load_lds_dwordx4 v[236:237], off
	s_mov_b32 m0, s50
	s_nop 0
	global_load_lds_dwordx4 v[238:239], off
	s_waitcnt vmcnt(8)
	s_waitcnt lgkmcnt(0)
	s_barrier
	s_setprio 1
	s_waitcnt lgkmcnt(0)
	v_mfma_f32_16x16x32_bf16 v[60:63], v[64:67], v[204:207], v[60:63]
	v_mfma_f32_16x16x32_bf16 v[56:59], v[76:79], v[204:207], v[56:59]
	v_mfma_f32_16x16x32_bf16 v[44:47], v[64:67], v[212:215], v[44:47]
	v_mfma_f32_16x16x32_bf16 v[40:43], v[76:79], v[212:215], v[40:43]
	v_mfma_f32_16x16x32_bf16 v[28:31], v[64:67], v[220:223], v[28:31]
	v_mfma_f32_16x16x32_bf16 v[24:27], v[76:79], v[220:223], v[24:27]
	v_mfma_f32_16x16x32_bf16 v[12:15], v[64:67], v[228:231], v[12:15]
	v_mfma_f32_16x16x32_bf16 v[8:11], v[76:79], v[228:231], v[8:11]
	v_mfma_f32_16x16x32_bf16 v[60:63], v[68:71], v[208:211], v[60:63]
	v_mfma_f32_16x16x32_bf16 v[56:59], v[80:83], v[208:211], v[56:59]
	v_mfma_f32_16x16x32_bf16 v[44:47], v[68:71], v[216:219], v[44:47]
	v_mfma_f32_16x16x32_bf16 v[40:43], v[80:83], v[216:219], v[40:43]
	v_mfma_f32_16x16x32_bf16 v[28:31], v[68:71], v[224:227], v[28:31]
	v_mfma_f32_16x16x32_bf16 v[24:27], v[80:83], v[224:227], v[24:27]
	v_mfma_f32_16x16x32_bf16 v[12:15], v[68:71], v[232:235], v[12:15]
	v_mfma_f32_16x16x32_bf16 v[8:11], v[80:83], v[232:235], v[8:11]
	s_setprio 0
	s_setprio 1
	v_mfma_f32_16x16x32_bf16 v[52:55], v[184:187], v[204:207], v[52:55]
	v_mfma_f32_16x16x32_bf16 v[48:51], v[192:195], v[204:207], v[48:51]
	v_mfma_f32_16x16x32_bf16 v[36:39], v[184:187], v[212:215], v[36:39]
	v_mfma_f32_16x16x32_bf16 v[32:35], v[192:195], v[212:215], v[32:35]
	v_mfma_f32_16x16x32_bf16 v[20:23], v[184:187], v[220:223], v[20:23]
	v_mfma_f32_16x16x32_bf16 v[16:19], v[192:195], v[220:223], v[16:19]
	v_mfma_f32_16x16x32_bf16 v[4:7], v[184:187], v[228:231], v[4:7]
	v_mfma_f32_16x16x32_bf16 v[0:3], v[192:195], v[228:231], v[0:3]
	v_mfma_f32_16x16x32_bf16 v[52:55], v[188:191], v[208:211], v[52:55]
	v_mfma_f32_16x16x32_bf16 v[48:51], v[200:203], v[208:211], v[48:51]
	v_mfma_f32_16x16x32_bf16 v[36:39], v[188:191], v[216:219], v[36:39]
	v_mfma_f32_16x16x32_bf16 v[32:35], v[200:203], v[216:219], v[32:35]
	v_mfma_f32_16x16x32_bf16 v[20:23], v[188:191], v[224:227], v[20:23]
	v_mfma_f32_16x16x32_bf16 v[16:19], v[200:203], v[224:227], v[16:19]
	v_mfma_f32_16x16x32_bf16 v[4:7], v[188:191], v[232:235], v[4:7]
	v_mfma_f32_16x16x32_bf16 v[0:3], v[200:203], v[232:235], v[0:3]
	s_setprio 0
	s_barrier
	s_add_i32 s67, 0, 0x18000
	s_add_i32 s70, 0, 0x1c000
	v_add_u32_e32 v80, s67, v166
	v_add_u32_e32 v164, s70, v166
	ds_read_b128 v[64:67], v80
	ds_read_b128 v[68:71], v80 offset:1024
	ds_read_b128 v[76:79], v80 offset:2048
	ds_read_b128 v[80:83], v80 offset:3072
	ds_read_b128 v[184:187], v164
	ds_read_b128 v[188:191], v164 offset:1024
	ds_read_b128 v[192:195], v164 offset:2048
	ds_read_b128 v[200:203], v164 offset:3072
	s_add_u32 s42, s42, 0x40000
	s_addc_u32 s43, s43, 0
	s_mov_b32 m0, s51
	v_lshl_add_u64 v[240:241], s[42:43], 0, v[144:145]
	ds_read_b128 v[204:207], v178 offset:32768
	ds_read_b128 v[208:211], v178 offset:33792
	ds_read_b128 v[212:215], v178 offset:34816
	ds_read_b128 v[216:219], v178 offset:35840
	ds_read_b128 v[220:223], v178 offset:36864
	ds_read_b128 v[224:227], v178 offset:37888
	ds_read_b128 v[228:231], v178 offset:38912
	ds_read_b128 v[232:235], v178 offset:39936
	global_load_lds_dwordx4 v[240:241], off
	v_lshl_add_u64 v[240:241], s[42:43], 0, v[148:149]
	s_mov_b32 m0, s52
	s_nop 0
	global_load_lds_dwordx4 v[240:241], off
	s_waitcnt vmcnt(8)
	s_waitcnt lgkmcnt(0)
	s_barrier
	s_setprio 1
	s_waitcnt lgkmcnt(0)
	v_mfma_f32_16x16x32_bf16 v[140:143], v[64:67], v[204:207], v[140:143]
	v_mfma_f32_16x16x32_bf16 v[132:135], v[76:79], v[204:207], v[132:135]
	v_mfma_f32_16x16x32_bf16 v[124:127], v[64:67], v[212:215], v[124:127]
	v_mfma_f32_16x16x32_bf16 v[120:123], v[76:79], v[212:215], v[120:123]
	v_mfma_f32_16x16x32_bf16 v[108:111], v[64:67], v[220:223], v[108:111]
	v_mfma_f32_16x16x32_bf16 v[104:107], v[76:79], v[220:223], v[104:107]
	v_mfma_f32_16x16x32_bf16 v[92:95], v[64:67], v[228:231], v[92:95]
	v_mfma_f32_16x16x32_bf16 v[88:91], v[76:79], v[228:231], v[88:91]
	v_mfma_f32_16x16x32_bf16 v[140:143], v[68:71], v[208:211], v[140:143]
	v_mfma_f32_16x16x32_bf16 v[132:135], v[80:83], v[208:211], v[132:135]
	v_mfma_f32_16x16x32_bf16 v[124:127], v[68:71], v[216:219], v[124:127]
	v_mfma_f32_16x16x32_bf16 v[120:123], v[80:83], v[216:219], v[120:123]
	v_mfma_f32_16x16x32_bf16 v[108:111], v[68:71], v[224:227], v[108:111]
	v_mfma_f32_16x16x32_bf16 v[104:107], v[80:83], v[224:227], v[104:107]
	v_mfma_f32_16x16x32_bf16 v[92:95], v[68:71], v[232:235], v[92:95]
	v_mfma_f32_16x16x32_bf16 v[88:91], v[80:83], v[232:235], v[88:91]
	s_setprio 0
	s_setprio 1
	v_mfma_f32_16x16x32_bf16 v[136:139], v[184:187], v[204:207], v[136:139]
	v_mfma_f32_16x16x32_bf16 v[128:131], v[192:195], v[204:207], v[128:131]
	v_mfma_f32_16x16x32_bf16 v[116:119], v[184:187], v[212:215], v[116:119]
	v_mfma_f32_16x16x32_bf16 v[112:115], v[192:195], v[212:215], v[112:115]
	v_mfma_f32_16x16x32_bf16 v[100:103], v[184:187], v[220:223], v[100:103]
	v_mfma_f32_16x16x32_bf16 v[96:99], v[192:195], v[220:223], v[96:99]
	v_mfma_f32_16x16x32_bf16 v[84:87], v[184:187], v[228:231], v[84:87]
	v_mfma_f32_16x16x32_bf16 v[72:75], v[192:195], v[228:231], v[72:75]
	v_mfma_f32_16x16x32_bf16 v[136:139], v[188:191], v[208:211], v[136:139]
	v_mfma_f32_16x16x32_bf16 v[128:131], v[200:203], v[208:211], v[128:131]
	v_mfma_f32_16x16x32_bf16 v[116:119], v[188:191], v[216:219], v[116:119]
	v_mfma_f32_16x16x32_bf16 v[112:115], v[200:203], v[216:219], v[112:115]
	v_mfma_f32_16x16x32_bf16 v[100:103], v[188:191], v[224:227], v[100:103]
	v_mfma_f32_16x16x32_bf16 v[96:99], v[200:203], v[224:227], v[96:99]
	v_mfma_f32_16x16x32_bf16 v[84:87], v[188:191], v[232:235], v[84:87]
	v_mfma_f32_16x16x32_bf16 v[72:75], v[200:203], v[232:235], v[72:75]
	s_setprio 0
	s_barrier
	s_add_i32 s42, s67, s48
	v_lshl_add_u64 v[162:163], v[162:163], 0, s[12:13]
	s_mov_b32 m0, s42
	ds_read_b128 v[204:207], v178 offset:49152
	ds_read_b128 v[208:211], v178 offset:50176
	ds_read_b128 v[212:215], v178 offset:51200
	ds_read_b128 v[216:219], v178 offset:52224
	ds_read_b128 v[220:223], v178 offset:53248
	ds_read_b128 v[224:227], v178 offset:54272
	ds_read_b128 v[228:231], v178 offset:55296
	ds_read_b128 v[232:235], v178 offset:56320
	global_load_lds_dwordx4 v[162:163], off
	s_add_i32 m0, s42, 0x2000
	s_add_u32 s26, s26, 0x40080
	v_lshl_add_u64 v[162:163], v[196:197], 0, s[12:13]
	s_addc_u32 s27, s27, 0
	s_add_i32 s42, s70, s48
	global_load_lds_dwordx4 v[162:163], off
	v_lshl_add_u64 v[162:163], s[26:27], 0, v[146:147]
	s_mov_b32 m0, s42
	s_nop 0
	global_load_lds_dwordx4 v[162:163], off
	v_lshl_add_u64 v[162:163], s[26:27], 0, v[150:151]
	s_add_i32 m0, s42, 0x2000
	s_nop 0
	global_load_lds_dwordx4 v[162:163], off
	v_lshl_add_u64 v[162:163], v[236:237], 0, s[12:13]
	s_mov_b32 m0, s55
	s_nop 0
	global_load_lds_dwordx4 v[162:163], off
	v_lshl_add_u64 v[162:163], v[238:239], 0, s[12:13]
	s_mov_b32 m0, s56
	s_nop 0
	global_load_lds_dwordx4 v[162:163], off
	s_add_i32 s66, s66, 2
	s_add_u32 s24, s24, 0x100
	s_addc_u32 s25, s25, 0
	s_add_u32 s19, s19, 0x100
	s_addc_u32 s65, s65, 0
	s_waitcnt vmcnt(8)
	s_waitcnt lgkmcnt(0)
	s_barrier
	s_setprio 1
	s_waitcnt lgkmcnt(0)
	v_mfma_f32_16x16x32_bf16 v[60:63], v[64:67], v[204:207], v[60:63]
	v_mfma_f32_16x16x32_bf16 v[56:59], v[76:79], v[204:207], v[56:59]
	v_mfma_f32_16x16x32_bf16 v[44:47], v[64:67], v[212:215], v[44:47]
	v_mfma_f32_16x16x32_bf16 v[40:43], v[76:79], v[212:215], v[40:43]
	v_mfma_f32_16x16x32_bf16 v[28:31], v[64:67], v[220:223], v[28:31]
	v_mfma_f32_16x16x32_bf16 v[24:27], v[76:79], v[220:223], v[24:27]
	v_mfma_f32_16x16x32_bf16 v[12:15], v[64:67], v[228:231], v[12:15]
	v_mfma_f32_16x16x32_bf16 v[8:11], v[76:79], v[228:231], v[8:11]
	v_mfma_f32_16x16x32_bf16 v[60:63], v[68:71], v[208:211], v[60:63]
	v_mfma_f32_16x16x32_bf16 v[56:59], v[80:83], v[208:211], v[56:59]
	v_mfma_f32_16x16x32_bf16 v[44:47], v[68:71], v[216:219], v[44:47]
	v_mfma_f32_16x16x32_bf16 v[40:43], v[80:83], v[216:219], v[40:43]
	v_mfma_f32_16x16x32_bf16 v[28:31], v[68:71], v[224:227], v[28:31]
	v_mfma_f32_16x16x32_bf16 v[24:27], v[80:83], v[224:227], v[24:27]
	v_mfma_f32_16x16x32_bf16 v[12:15], v[68:71], v[232:235], v[12:15]
	v_mfma_f32_16x16x32_bf16 v[8:11], v[80:83], v[232:235], v[8:11]
	s_setprio 0
	s_setprio 1
	v_mfma_f32_16x16x32_bf16 v[52:55], v[184:187], v[204:207], v[52:55]
	v_mfma_f32_16x16x32_bf16 v[48:51], v[192:195], v[204:207], v[48:51]
	v_mfma_f32_16x16x32_bf16 v[36:39], v[184:187], v[212:215], v[36:39]
	v_mfma_f32_16x16x32_bf16 v[32:35], v[192:195], v[212:215], v[32:35]
	v_mfma_f32_16x16x32_bf16 v[20:23], v[184:187], v[220:223], v[20:23]
	v_mfma_f32_16x16x32_bf16 v[16:19], v[192:195], v[220:223], v[16:19]
	v_mfma_f32_16x16x32_bf16 v[4:7], v[184:187], v[228:231], v[4:7]
	v_mfma_f32_16x16x32_bf16 v[0:3], v[192:195], v[228:231], v[0:3]
	v_mfma_f32_16x16x32_bf16 v[52:55], v[188:191], v[208:211], v[52:55]
	v_mfma_f32_16x16x32_bf16 v[48:51], v[200:203], v[208:211], v[48:51]
	v_mfma_f32_16x16x32_bf16 v[36:39], v[188:191], v[216:219], v[36:39]
	v_mfma_f32_16x16x32_bf16 v[32:35], v[200:203], v[216:219], v[32:35]
	v_mfma_f32_16x16x32_bf16 v[20:23], v[188:191], v[224:227], v[20:23]
	v_mfma_f32_16x16x32_bf16 v[16:19], v[200:203], v[224:227], v[16:19]
	v_mfma_f32_16x16x32_bf16 v[4:7], v[188:191], v[232:235], v[4:7]
	v_mfma_f32_16x16x32_bf16 v[0:3], v[200:203], v[232:235], v[0:3]
	s_setprio 0
	s_barrier
	s_cmp_gt_u32 s66, 13
	s_cbranch_scc0 .LBB0_1671
	s_and_b64 vcc, exec, s[14:15]
	s_cbranch_vccz .LBB0_1674
	s_barrier

.LBB0_1786:
	ds_read_b128 v[144:147], v167
	ds_read_b128 v[148:151], v167 offset:1024
	ds_read_b128 v[152:155], v167 offset:2048
	ds_read_b128 v[156:159], v167 offset:3072
	ds_read_b128 v[160:163], v168
	ds_read_b128 v[170:173], v168 offset:1024
	ds_read_b128 v[174:177], v168 offset:2048
	ds_read_b128 v[178:181], v168 offset:3072
	s_add_u32 s16, s14, 0xfff50080
	s_addc_u32 s17, s15, -1
	s_cmp_eq_u32 s50, 40
	s_cselect_b32 s19, s3, s17
	s_cselect_b32 s18, s2, s16
	s_cselect_b32 s17, s13, s49
	s_cselect_b32 s16, s12, s48
	v_lshl_add_u64 v[214:215], s[14:15], 0, v[136:137]
	s_add_i32 m0, s24, 0xc000
	ds_read_b128 v[182:185], v169
	ds_read_b128 v[186:189], v169 offset:1024
	ds_read_b128 v[190:193], v169 offset:2048
	ds_read_b128 v[194:197], v169 offset:3072
	ds_read_b128 v[198:201], v169 offset:4096
	ds_read_b128 v[202:205], v169 offset:5120
	ds_read_b128 v[206:209], v169 offset:6144
	ds_read_b128 v[210:213], v169 offset:7168
	global_load_lds_dwordx4 v[214:215], off
	v_lshl_add_u64 v[214:215], s[14:15], 0, v[138:139]
	s_add_i32 m0, s24, 0xe000
	s_nop 0
	global_load_lds_dwordx4 v[214:215], off
	s_waitcnt vmcnt(8)
	s_waitcnt lgkmcnt(0)
	s_barrier
	s_setprio 1
	s_waitcnt lgkmcnt(0)
	v_mfma_f32_16x16x32_bf16 v[124:127], v[144:147], v[182:185], v[124:127]
	v_mfma_f32_16x16x32_bf16 v[120:123], v[152:155], v[182:185], v[120:123]
	v_mfma_f32_16x16x32_bf16 v[108:111], v[144:147], v[190:193], v[108:111]
	v_mfma_f32_16x16x32_bf16 v[104:107], v[152:155], v[190:193], v[104:107]
	v_mfma_f32_16x16x32_bf16 v[92:95], v[144:147], v[198:201], v[92:95]
	v_mfma_f32_16x16x32_bf16 v[88:91], v[152:155], v[198:201], v[88:91]
	v_mfma_f32_16x16x32_bf16 v[76:79], v[144:147], v[206:209], v[76:79]
	v_mfma_f32_16x16x32_bf16 v[72:75], v[152:155], v[206:209], v[72:75]
	v_mfma_f32_16x16x32_bf16 v[124:127], v[148:151], v[186:189], v[124:127]
	v_mfma_f32_16x16x32_bf16 v[120:123], v[156:159], v[186:189], v[120:123]
	v_mfma_f32_16x16x32_bf16 v[108:111], v[148:151], v[194:197], v[108:111]
	v_mfma_f32_16x16x32_bf16 v[104:107], v[156:159], v[194:197], v[104:107]
	v_mfma_f32_16x16x32_bf16 v[92:95], v[148:151], v[202:205], v[92:95]
	v_mfma_f32_16x16x32_bf16 v[88:91], v[156:159], v[202:205], v[88:91]
	v_mfma_f32_16x16x32_bf16 v[76:79], v[148:151], v[210:213], v[76:79]
	v_mfma_f32_16x16x32_bf16 v[72:75], v[156:159], v[210:213], v[72:75]
	s_setprio 0
	s_setprio 1
	v_mfma_f32_16x16x32_bf16 v[116:119], v[160:163], v[182:185], v[116:119]
	v_mfma_f32_16x16x32_bf16 v[112:115], v[174:177], v[182:185], v[112:115]
	v_mfma_f32_16x16x32_bf16 v[100:103], v[160:163], v[190:193], v[100:103]
	v_mfma_f32_16x16x32_bf16 v[96:99], v[174:177], v[190:193], v[96:99]
	v_mfma_f32_16x16x32_bf16 v[84:87], v[160:163], v[198:201], v[84:87]
	v_mfma_f32_16x16x32_bf16 v[80:83], v[174:177], v[198:201], v[80:83]
	v_mfma_f32_16x16x32_bf16 v[68:71], v[160:163], v[206:209], v[68:71]
	v_mfma_f32_16x16x32_bf16 v[64:67], v[174:177], v[206:209], v[64:67]
	v_mfma_f32_16x16x32_bf16 v[116:119], v[170:173], v[186:189], v[116:119]
	v_mfma_f32_16x16x32_bf16 v[112:115], v[178:181], v[186:189], v[112:115]
	v_mfma_f32_16x16x32_bf16 v[100:103], v[170:173], v[194:197], v[100:103]
	v_mfma_f32_16x16x32_bf16 v[96:99], v[178:181], v[194:197], v[96:99]
	v_mfma_f32_16x16x32_bf16 v[84:87], v[170:173], v[202:205], v[84:87]
	v_mfma_f32_16x16x32_bf16 v[80:83], v[178:181], v[202:205], v[80:83]
	v_mfma_f32_16x16x32_bf16 v[68:71], v[170:173], v[210:213], v[68:71]
	v_mfma_f32_16x16x32_bf16 v[64:67], v[178:181], v[210:213], v[64:67]
	s_setprio 0
	s_barrier
	s_add_i32 s51, s41, s23
	v_lshl_add_u64 v[214:215], s[16:17], 0, v[130:131]
	s_mov_b32 m0, s51
	ds_read_b128 v[182:185], v169 offset:16384
	ds_read_b128 v[186:189], v169 offset:17408
	ds_read_b128 v[190:193], v169 offset:18432
	ds_read_b128 v[194:197], v169 offset:19456
	ds_read_b128 v[198:201], v169 offset:20480
	ds_read_b128 v[202:205], v169 offset:21504
	ds_read_b128 v[206:209], v169 offset:22528
	ds_read_b128 v[210:213], v169 offset:23552
	global_load_lds_dwordx4 v[214:215], off
	s_add_i32 m0, s51, 0x2000
	s_add_u32 s52, s16, 0xb0000
	v_lshl_add_u64 v[216:217], s[16:17], 0, v[134:135]
	s_addc_u32 s53, s17, 0
	s_add_i32 s51, s42, s23
	global_load_lds_dwordx4 v[216:217], off
	v_lshl_add_u64 v[218:219], s[52:53], 0, v[130:131]
	s_mov_b32 m0, s51
	v_lshl_add_u64 v[220:221], s[18:19], 0, v[132:133]
	global_load_lds_dwordx4 v[218:219], off
	v_lshl_add_u64 v[218:219], s[52:53], 0, v[134:135]
	s_add_i32 m0, s51, 0x2000
	s_nop 0
	global_load_lds_dwordx4 v[218:219], off
	v_lshl_add_u64 v[218:219], s[18:19], 0, v[128:129]
	s_mov_b32 m0, s24
	s_nop 0
	global_load_lds_dwordx4 v[218:219], off
	s_mov_b32 m0, s25
	s_nop 0
	global_load_lds_dwordx4 v[220:221], off
	s_waitcnt vmcnt(8)
	s_waitcnt lgkmcnt(0)
	s_barrier
	s_setprio 1
	s_waitcnt lgkmcnt(0)
	v_mfma_f32_16x16x32_bf16 v[60:63], v[144:147], v[182:185], v[60:63]
	v_mfma_f32_16x16x32_bf16 v[56:59], v[152:155], v[182:185], v[56:59]
	v_mfma_f32_16x16x32_bf16 v[44:47], v[144:147], v[190:193], v[44:47]
	v_mfma_f32_16x16x32_bf16 v[40:43], v[152:155], v[190:193], v[40:43]
	v_mfma_f32_16x16x32_bf16 v[28:31], v[144:147], v[198:201], v[28:31]
	v_mfma_f32_16x16x32_bf16 v[24:27], v[152:155], v[198:201], v[24:27]
	v_mfma_f32_16x16x32_bf16 v[12:15], v[144:147], v[206:209], v[12:15]
	v_mfma_f32_16x16x32_bf16 v[8:11], v[152:155], v[206:209], v[8:11]
	v_mfma_f32_16x16x32_bf16 v[60:63], v[148:151], v[186:189], v[60:63]
	v_mfma_f32_16x16x32_bf16 v[56:59], v[156:159], v[186:189], v[56:59]
	v_mfma_f32_16x16x32_bf16 v[44:47], v[148:151], v[194:197], v[44:47]
	v_mfma_f32_16x16x32_bf16 v[40:43], v[156:159], v[194:197], v[40:43]
	v_mfma_f32_16x16x32_bf16 v[28:31], v[148:151], v[202:205], v[28:31]
	v_mfma_f32_16x16x32_bf16 v[24:27], v[156:159], v[202:205], v[24:27]
	v_mfma_f32_16x16x32_bf16 v[12:15], v[148:151], v[210:213], v[12:15]
	v_mfma_f32_16x16x32_bf16 v[8:11], v[156:159], v[210:213], v[8:11]
	s_setprio 0
	s_setprio 1
	v_mfma_f32_16x16x32_bf16 v[52:55], v[160:163], v[182:185], v[52:55]
	v_mfma_f32_16x16x32_bf16 v[48:51], v[174:177], v[182:185], v[48:51]
	v_mfma_f32_16x16x32_bf16 v[36:39], v[160:163], v[190:193], v[36:39]
	v_mfma_f32_16x16x32_bf16 v[32:35], v[174:177], v[190:193], v[32:35]
	v_mfma_f32_16x16x32_bf16 v[20:23], v[160:163], v[198:201], v[20:23]
	v_mfma_f32_16x16x32_bf16 v[16:19], v[174:177], v[198:201], v[16:19]
	v_mfma_f32_16x16x32_bf16 v[4:7], v[160:163], v[206:209], v[4:7]
	v_mfma_f32_16x16x32_bf16 v[0:3], v[174:177], v[206:209], v[0:3]
	v_mfma_f32_16x16x32_bf16 v[52:55], v[170:173], v[186:189], v[52:55]
	v_mfma_f32_16x16x32_bf16 v[48:51], v[178:181], v[186:189], v[48:51]
	v_mfma_f32_16x16x32_bf16 v[36:39], v[170:173], v[194:197], v[36:39]
	v_mfma_f32_16x16x32_bf16 v[32:35], v[178:181], v[194:197], v[32:35]
	v_mfma_f32_16x16x32_bf16 v[20:23], v[170:173], v[202:205], v[20:23]
	v_mfma_f32_16x16x32_bf16 v[16:19], v[178:181], v[202:205], v[16:19]
	v_mfma_f32_16x16x32_bf16 v[4:7], v[170:173], v[210:213], v[4:7]
	v_mfma_f32_16x16x32_bf16 v[0:3], v[178:181], v[210:213], v[0:3]
	s_setprio 0
	s_barrier
	s_add_i32 s51, 0, 0x18000
	s_add_i32 s52, 0, 0x1c000
	v_add_u32_e32 v156, s51, v165
	v_add_u32_e32 v178, s52, v165
	ds_read_b128 v[144:147], v156
	ds_read_b128 v[148:151], v156 offset:1024
	ds_read_b128 v[152:155], v156 offset:2048
	ds_read_b128 v[156:159], v156 offset:3072
	ds_read_b128 v[160:163], v178
	ds_read_b128 v[170:173], v178 offset:1024
	ds_read_b128 v[174:177], v178 offset:2048
	ds_read_b128 v[178:181], v178 offset:3072
	s_add_u32 s18, s18, 0xb0000
	s_addc_u32 s19, s19, 0
	s_mov_b32 m0, s26
	v_lshl_add_u64 v[222:223], s[18:19], 0, v[128:129]
	ds_read_b128 v[182:185], v169 offset:32768
	ds_read_b128 v[186:189], v169 offset:33792
	ds_read_b128 v[190:193], v169 offset:34816
	ds_read_b128 v[194:197], v169 offset:35840
	ds_read_b128 v[198:201], v169 offset:36864
	ds_read_b128 v[202:205], v169 offset:37888
	ds_read_b128 v[206:209], v169 offset:38912
	ds_read_b128 v[210:213], v169 offset:39936
	global_load_lds_dwordx4 v[222:223], off
	v_lshl_add_u64 v[222:223], s[18:19], 0, v[132:133]
	s_mov_b32 m0, s27
	s_nop 0
	global_load_lds_dwordx4 v[222:223], off
	s_waitcnt vmcnt(8)
	s_waitcnt lgkmcnt(0)
	s_barrier
	s_setprio 1
	s_waitcnt lgkmcnt(0)
	v_mfma_f32_16x16x32_bf16 v[124:127], v[144:147], v[182:185], v[124:127]
	v_mfma_f32_16x16x32_bf16 v[120:123], v[152:155], v[182:185], v[120:123]
	v_mfma_f32_16x16x32_bf16 v[108:111], v[144:147], v[190:193], v[108:111]
	v_mfma_f32_16x16x32_bf16 v[104:107], v[152:155], v[190:193], v[104:107]
	v_mfma_f32_16x16x32_bf16 v[92:95], v[144:147], v[198:201], v[92:95]
	v_mfma_f32_16x16x32_bf16 v[88:91], v[152:155], v[198:201], v[88:91]
	v_mfma_f32_16x16x32_bf16 v[76:79], v[144:147], v[206:209], v[76:79]
	v_mfma_f32_16x16x32_bf16 v[72:75], v[152:155], v[206:209], v[72:75]
	v_mfma_f32_16x16x32_bf16 v[124:127], v[148:151], v[186:189], v[124:127]
	v_mfma_f32_16x16x32_bf16 v[120:123], v[156:159], v[186:189], v[120:123]
	v_mfma_f32_16x16x32_bf16 v[108:111], v[148:151], v[194:197], v[108:111]
	v_mfma_f32_16x16x32_bf16 v[104:107], v[156:159], v[194:197], v[104:107]
	v_mfma_f32_16x16x32_bf16 v[92:95], v[148:151], v[202:205], v[92:95]
	v_mfma_f32_16x16x32_bf16 v[88:91], v[156:159], v[202:205], v[88:91]
	v_mfma_f32_16x16x32_bf16 v[76:79], v[148:151], v[210:213], v[76:79]
	v_mfma_f32_16x16x32_bf16 v[72:75], v[156:159], v[210:213], v[72:75]
	s_setprio 0
	s_setprio 1
	v_mfma_f32_16x16x32_bf16 v[116:119], v[160:163], v[182:185], v[116:119]
	v_mfma_f32_16x16x32_bf16 v[112:115], v[174:177], v[182:185], v[112:115]
	v_mfma_f32_16x16x32_bf16 v[100:103], v[160:163], v[190:193], v[100:103]
	v_mfma_f32_16x16x32_bf16 v[96:99], v[174:177], v[190:193], v[96:99]
	v_mfma_f32_16x16x32_bf16 v[84:87], v[160:163], v[198:201], v[84:87]
	v_mfma_f32_16x16x32_bf16 v[80:83], v[174:177], v[198:201], v[80:83]
	v_mfma_f32_16x16x32_bf16 v[68:71], v[160:163], v[206:209], v[68:71]
	v_mfma_f32_16x16x32_bf16 v[64:67], v[174:177], v[206:209], v[64:67]
	v_mfma_f32_16x16x32_bf16 v[116:119], v[170:173], v[186:189], v[116:119]
	v_mfma_f32_16x16x32_bf16 v[112:115], v[178:181], v[186:189], v[112:115]
	v_mfma_f32_16x16x32_bf16 v[100:103], v[170:173], v[194:197], v[100:103]
	v_mfma_f32_16x16x32_bf16 v[96:99], v[178:181], v[194:197], v[96:99]
	v_mfma_f32_16x16x32_bf16 v[84:87], v[170:173], v[202:205], v[84:87]
	v_mfma_f32_16x16x32_bf16 v[80:83], v[178:181], v[202:205], v[80:83]
	v_mfma_f32_16x16x32_bf16 v[68:71], v[170:173], v[210:213], v[68:71]
	v_mfma_f32_16x16x32_bf16 v[64:67], v[178:181], v[210:213], v[64:67]
	s_setprio 0
	s_barrier
	s_add_i32 s18, s51, s23
	v_lshl_add_u64 v[214:215], v[214:215], 0, s[6:7]
	s_mov_b32 m0, s18
	ds_read_b128 v[182:185], v169 offset:49152
	ds_read_b128 v[186:189], v169 offset:50176
	ds_read_b128 v[190:193], v169 offset:51200
	ds_read_b128 v[194:197], v169 offset:52224
	ds_read_b128 v[198:201], v169 offset:53248
	ds_read_b128 v[202:205], v169 offset:54272
	ds_read_b128 v[206:209], v169 offset:55296
	ds_read_b128 v[210:213], v169 offset:56320
	global_load_lds_dwordx4 v[214:215], off
	s_add_i32 m0, s18, 0x2000
	s_add_u32 s16, s16, 0xb0080
	v_lshl_add_u64 v[214:215], v[216:217], 0, s[6:7]
	s_addc_u32 s17, s17, 0
	s_add_i32 s18, s52, s23
	global_load_lds_dwordx4 v[214:215], off
	v_lshl_add_u64 v[214:215], s[16:17], 0, v[130:131]
	s_mov_b32 m0, s18
	s_nop 0
	global_load_lds_dwordx4 v[214:215], off
	v_lshl_add_u64 v[214:215], s[16:17], 0, v[134:135]
	s_add_i32 m0, s18, 0x2000
	s_nop 0
	global_load_lds_dwordx4 v[214:215], off
	v_lshl_add_u64 v[214:215], v[218:219], 0, s[6:7]
	s_mov_b32 m0, s35
	s_nop 0
	global_load_lds_dwordx4 v[214:215], off
	v_lshl_add_u64 v[214:215], v[220:221], 0, s[6:7]
	s_mov_b32 m0, s39
	s_nop 0
	global_load_lds_dwordx4 v[214:215], off
	s_add_i32 s50, s50, 2
	s_add_u32 s14, s14, 0x100
	s_addc_u32 s15, s15, 0
	s_add_u32 s48, s48, 0x100
	s_addc_u32 s49, s49, 0
	s_waitcnt vmcnt(8)
	s_waitcnt lgkmcnt(0)
	s_barrier
	s_setprio 1
	s_waitcnt lgkmcnt(0)
	v_mfma_f32_16x16x32_bf16 v[60:63], v[144:147], v[182:185], v[60:63]
	v_mfma_f32_16x16x32_bf16 v[56:59], v[152:155], v[182:185], v[56:59]
	v_mfma_f32_16x16x32_bf16 v[44:47], v[144:147], v[190:193], v[44:47]
	v_mfma_f32_16x16x32_bf16 v[40:43], v[152:155], v[190:193], v[40:43]
	v_mfma_f32_16x16x32_bf16 v[28:31], v[144:147], v[198:201], v[28:31]
	v_mfma_f32_16x16x32_bf16 v[24:27], v[152:155], v[198:201], v[24:27]
	v_mfma_f32_16x16x32_bf16 v[12:15], v[144:147], v[206:209], v[12:15]
	v_mfma_f32_16x16x32_bf16 v[8:11], v[152:155], v[206:209], v[8:11]
	v_mfma_f32_16x16x32_bf16 v[60:63], v[148:151], v[186:189], v[60:63]
	v_mfma_f32_16x16x32_bf16 v[56:59], v[156:159], v[186:189], v[56:59]
	v_mfma_f32_16x16x32_bf16 v[44:47], v[148:151], v[194:197], v[44:47]
	v_mfma_f32_16x16x32_bf16 v[40:43], v[156:159], v[194:197], v[40:43]
	v_mfma_f32_16x16x32_bf16 v[28:31], v[148:151], v[202:205], v[28:31]
	v_mfma_f32_16x16x32_bf16 v[24:27], v[156:159], v[202:205], v[24:27]
	v_mfma_f32_16x16x32_bf16 v[12:15], v[148:151], v[210:213], v[12:15]
	v_mfma_f32_16x16x32_bf16 v[8:11], v[156:159], v[210:213], v[8:11]
	s_setprio 0
	s_setprio 1
	v_mfma_f32_16x16x32_bf16 v[52:55], v[160:163], v[182:185], v[52:55]
	v_mfma_f32_16x16x32_bf16 v[48:51], v[174:177], v[182:185], v[48:51]
	v_mfma_f32_16x16x32_bf16 v[36:39], v[160:163], v[190:193], v[36:39]
	v_mfma_f32_16x16x32_bf16 v[32:35], v[174:177], v[190:193], v[32:35]
	v_mfma_f32_16x16x32_bf16 v[20:23], v[160:163], v[198:201], v[20:23]
	v_mfma_f32_16x16x32_bf16 v[16:19], v[174:177], v[198:201], v[16:19]
	v_mfma_f32_16x16x32_bf16 v[4:7], v[160:163], v[206:209], v[4:7]
	v_mfma_f32_16x16x32_bf16 v[0:3], v[174:177], v[206:209], v[0:3]
	v_mfma_f32_16x16x32_bf16 v[52:55], v[170:173], v[186:189], v[52:55]
	v_mfma_f32_16x16x32_bf16 v[48:51], v[178:181], v[186:189], v[48:51]
	v_mfma_f32_16x16x32_bf16 v[36:39], v[170:173], v[194:197], v[36:39]
	v_mfma_f32_16x16x32_bf16 v[32:35], v[178:181], v[194:197], v[32:35]
	v_mfma_f32_16x16x32_bf16 v[20:23], v[170:173], v[202:205], v[20:23]
	v_mfma_f32_16x16x32_bf16 v[16:19], v[178:181], v[202:205], v[16:19]
	v_mfma_f32_16x16x32_bf16 v[4:7], v[170:173], v[210:213], v[4:7]
	v_mfma_f32_16x16x32_bf16 v[0:3], v[178:181], v[210:213], v[0:3]
	s_setprio 0
	s_barrier
	s_cmp_gt_u32 s50, 41
	s_cbranch_scc0 .LBB0_1786
	s_and_b64 vcc, exec, s[8:9]
	s_cbranch_vccz .LBB0_1789
	s_barrier
